# v28 + write-through (sc1) stores in the preparation phase so the first grid barrier's L2 write-back finds little dirty data
# baseline (speedup 1.0000x reference)
; __device__ __forceinline__ unsigned cvt_pk_bf16(float lo, float hi) { f32x2 v = {lo, hi}; bf16x2_t b = __builtin_convertvector(v, bf16x2_t); return __builtin_bit_cast(unsigned, b); }
; #define LAS __attribute__((address_space(3)))
; #define LDS_WAIT() asm volatile("s_waitcnt lgkmcnt(0)" ::: "memory")
; template <int MODE> __device__ __forceinline__ void transpose_item(const float* W, int ldw, int K, int N, const float* ks, bf16_t* WT, LAS float* scr, int item, int lane) {
;     ...
;         for (int i = 0; i < 32; ++i) { const int kk = 2 * i + (lane >> 5); float x = v[i]; if (ks) x *= ks[k0 + kk]; scr[kk * 33 + (lane & 31)] = x; } }
;     LDS_WAIT(); asm volatile("" ::: "memory");
;     const int c = lane & 7;
; #pragma unroll
;     for (int j = 0; j < 4; ++j) { const int n = (lane >> 3) + 8 * j; const LAS float* s = scr + (8 * c) * 33 + n;
;         u32x4 o; o.x = cvt_pk_bf16(s[0 * 33], s[1 * 33]); o.y = cvt_pk_bf16(s[2 * 33], s[3 * 33]); o.z = cvt_pk_bf16(s[4 * 33], s[5 * 33]); o.w = cvt_pk_bf16(s[6 * 33], s[7 * 33]);
;         *(u32x4*)(WT + (size_t)(n0 + n) * K + k0 + 8 * c) = o; }
.LBB0_10:
	ds_write2_b32 v34, v32, v33 offset0:140 offset1:206
	s_waitcnt lgkmcnt(0)
	ds_read2_b32 v[34:35], v53 offset0:33 offset1:41
	ds_read2_b32 v[36:37], v53 offset1:8
	ds_read2_b32 v[38:39], v53 offset0:66 offset1:74
	ds_read2_b32 v[40:41], v53 offset0:99 offset1:107
	ds_read2_b32 v[42:43], v53 offset0:132 offset1:140
	ds_read2_b32 v[44:45], v53 offset0:165 offset1:173
	ds_read2_b32 v[46:47], v53 offset0:198 offset1:206
	ds_read2_b32 v[48:49], v53 offset0:231 offset1:239
	v_add_u32_e32 v82, s0, v52
	v_ashrrev_i32_e32 v83, 31, v82
	v_lshl_add_u64 v[80:81], s[54:55], 1, v[28:29]
	v_lshlrev_b64 v[84:85], 11, v[82:83]
	s_waitcnt lgkmcnt(6)
	v_cvt_pk_bf16_f32 v30, v36, v34
	s_waitcnt lgkmcnt(4)
	v_cvt_pk_bf16_f32 v31, v38, v40
	s_waitcnt lgkmcnt(2)
	v_cvt_pk_bf16_f32 v32, v42, v44
	s_waitcnt lgkmcnt(0)
	v_cvt_pk_bf16_f32 v33, v46, v48
	v_lshl_add_u64 v[84:85], v[80:81], 0, v[84:85]
	v_add_u32_e32 v34, 8, v82
	global_store_dwordx4 v[84:85], v[30:33], off sc1
	s_nop 1
	v_cvt_pk_bf16_f32 v30, v37, v35
	v_ashrrev_i32_e32 v35, 31, v34
	v_cvt_pk_bf16_f32 v31, v39, v41
	v_cvt_pk_bf16_f32 v32, v43, v45
	v_cvt_pk_bf16_f32 v33, v47, v49
	v_lshlrev_b64 v[34:35], 11, v[34:35]
	ds_read2_b32 v[36:37], v53 offset0:49 offset1:57
	ds_read2_b32 v[38:39], v53 offset0:16 offset1:24
	ds_read2_b32 v[40:41], v53 offset0:82 offset1:90
	ds_read2_b32 v[42:43], v53 offset0:115 offset1:123
	ds_read2_b32 v[44:45], v53 offset0:148 offset1:156
	ds_read2_b32 v[46:47], v53 offset0:181 offset1:189
	ds_read2_b32 v[48:49], v53 offset0:214 offset1:222
	ds_read2_b32 v[84:85], v53 offset0:247 offset1:255
	v_lshl_add_u64 v[34:35], v[80:81], 0, v[34:35]
	global_store_dwordx4 v[34:35], v[30:33], off sc1
	v_add_u32_e32 v34, 16, v82
	v_ashrrev_i32_e32 v35, 31, v34
	v_lshlrev_b64 v[34:35], 11, v[34:35]
	s_waitcnt lgkmcnt(6)
	v_cvt_pk_bf16_f32 v30, v38, v36
	s_waitcnt lgkmcnt(4)
	v_cvt_pk_bf16_f32 v31, v40, v42
	s_waitcnt lgkmcnt(2)
	v_cvt_pk_bf16_f32 v32, v44, v46
	s_waitcnt lgkmcnt(0)
	v_cvt_pk_bf16_f32 v33, v48, v84
	v_lshl_add_u64 v[34:35], v[80:81], 0, v[34:35]
	global_store_dwordx4 v[34:35], v[30:33], off sc1
	v_add_u32_e32 v34, 24, v82
	v_ashrrev_i32_e32 v35, 31, v34
	v_lshlrev_b64 v[34:35], 11, v[34:35]
	v_cvt_pk_bf16_f32 v30, v39, v37
	v_cvt_pk_bf16_f32 v31, v41, v43
	v_cvt_pk_bf16_f32 v32, v45, v47
	v_cvt_pk_bf16_f32 v33, v49, v85
	v_lshl_add_u64 v[34:35], v[80:81], 0, v[34:35]
	global_store_dwordx4 v[34:35], v[30:33], off sc1
	s_waitcnt lgkmcnt(0)

; template <int MODE> __device__ __forceinline__ void transpose_item(const float* W, int ldw, int K, int N, const float* ks, bf16_t* WT, LAS float* scr, int item, int lane) {
;     const int nblk = N / 32, kb = item / nblk, nb = item % nblk, k0 = 64 * kb, n0 = 32 * nb;
;     const int sc = src_col<MODE>(n0 + (lane & 31));
;     { float v[32];
; #pragma unroll
;         for (int i = 0; i < 32; ++i) { const int kk = 2 * i + (lane >> 5); v[i] = (sc >= 0) ? W[(size_t)(k0 + kk) * ldw + sc] : 0.f; }
; #pragma unroll
;         for (int i = 0; i < 32; ++i) { const int kk = 2 * i + (lane >> 5); float x = v[i]; if (ks) x *= ks[k0 + kk]; scr[kk * 33 + (lane & 31)] = x; } }
; __device__ __forceinline__ void prep_phase(const Args& a, LAS unsigned char* lds, int vcu, int G, int wave, int lane) {
;     ...
;     for (int it = gw; it < NITEMS; it += NGW) {
;         int r = it;
;         if (r < I_UP) { transpose_item<1>(a.in[2], NUP, DM, NUP, a.in[1], (bf16_t*)(ws + WS_WUP1), scr, r, lane); continue; } r -= I_UP;
;         if (r < I_UP) { transpose_item<1>(a.in[21], NUP, DM, NUP, a.in[20], (bf16_t*)(ws + WS_WUP2), scr, r, lane); continue; } r -= I_UP;
;         if (r < I_DN) { transpose_item<0>(a.in[3], DM, DFF, DM, nullptr, (bf16_t*)(ws + WS_WDN1), scr, r, lane); continue; } r -= I_DN;
;         if (r < I_DN) { transpose_item<0>(a.in[22], DM, DFF, DM, nullptr, (bf16_t*)(ws + WS_WDN2), scr, r, lane); continue; } r -= I_DN;
;     ...
;         if (r < I_O) { transpose_item<0>(a.in[17], DM, 1024, DM, nullptr, (bf16_t*)(ws + WS_WON), scr, r, lane); continue; } r -= I_O;
;         if (r < I_O) { transpose_item<0>(a.in[18], DM, 1024, DM, nullptr, (bf16_t*)(ws + WS_WON) + 512, scr, r, lane); continue; } r -= I_O;
;         if (r < I_OUT) { transpose_item<0>(a.in[19], DM, DM, DM, nullptr, (bf16_t*)(ws + WS_WOUT), scr, r, lane); continue; } r -= I_OUT;
;         if (r < I_C1) { transpose_item<0>(a.in[13], 128, 2048, 128, nullptr, (bf16_t*)(ws + WS_CW1K), scr, r, lane); continue; } r -= I_C1;
;         if (r < I_C1) { transpose_item<0>(a.in[15], 128, 2048, 128, nullptr, (bf16_t*)(ws + WS_CW1V), scr, r, lane); continue; } r -= I_C1;
;         if (r < I_C2) { transpose_item<0>(a.in[14], 64, 128, 64, nullptr, (bf16_t*)(ws + WS_CW2K), scr, r, lane); continue; } r -= I_C2;
;         transpose_item<0>(a.in[16], 64, 128, 64, nullptr, (bf16_t*)(ws + WS_CW2V), scr, r, lane);
.LBB0_12:
	s_cmpk_gt_i32 s73, 0xaff
	s_mov_b64 s[2:3], -1
	s_cbranch_scc0 .LBB0_180
	s_cmpk_gt_u32 s73, 0x15ff
	s_cbranch_scc0 .LBB0_153
	s_cmpk_gt_u32 s73, 0x1b7f
	s_cbranch_scc0 .LBB0_150
	s_cmpk_gt_u32 s73, 0x20ff
	s_cbranch_scc0 .LBB0_147
	s_cmpk_gt_u32 s73, 0x2aff
	s_cbranch_scc0 .LBB0_42
	s_cmpk_gt_u32 s73, 0x2bff
	s_cbranch_scc0 .LBB0_39
	s_cmpk_gt_u32 s73, 0x2cff
	s_cbranch_scc0 .LBB0_36
	s_cmpk_gt_u32 s73, 0x2eff
	s_cbranch_scc0 .LBB0_33
	s_cmpk_gt_u32 s73, 0x2f7f
	s_cbranch_scc0 .LBB0_30
	s_cmpk_gt_u32 s73, 0x2fff
	s_cbranch_scc0 .LBB0_27
	s_cmpk_gt_u32 s73, 0x3003
	s_cbranch_scc0 .LBB0_24
	s_add_i32 s0, s73, 0xcffc
	s_and_b32 s1, s0, 0xffff
	s_add_i32 s2, s73, 0xcffa
	s_cmp_lt_u32 s1, 2
	s_cselect_b32 s0, s0, s2
	s_cmp_gt_u32 s1, 1
	s_cselect_b32 s1, 64, 0
	s_lshl_b32 s0, s0, 5
	s_and_b32 s0, s0, 0xffe0
	v_or_b32_e32 v30, s1, v2
	v_or_b32_e32 v4, s0, v1
	v_lshlrev_b32_e32 v30, 6, v30
	v_add_lshl_u32 v4, v4, v30, 2
	global_load_dword v30, v4, s[10:11]
	global_load_dword v31, v4, s[10:11] offset:512
	global_load_dword v32, v4, s[10:11] offset:1024
	global_load_dword v33, v4, s[10:11] offset:1536
	global_load_dword v34, v4, s[10:11] offset:2048
	global_load_dword v35, v4, s[10:11] offset:2560
	global_load_dword v36, v4, s[10:11] offset:3072
	global_load_dword v37, v4, s[10:11] offset:3584
	v_add_u32_e32 v38, 0x1000, v4
	v_add_u32_e32 v39, 0x1200, v4
	v_add_u32_e32 v40, 0x1400, v4
	v_add_u32_e32 v41, 0x1600, v4
	v_add_u32_e32 v42, 0x1800, v4
	v_add_u32_e32 v43, 0x1a00, v4
	v_add_u32_e32 v44, 0x1c00, v4
	v_add_u32_e32 v45, 0x1e00, v4
	v_add_u32_e32 v46, 0x2000, v4
	v_add_u32_e32 v47, 0x2200, v4
	v_add_u32_e32 v48, 0x2400, v4
	v_add_u32_e32 v49, 0x2600, v4
	v_add_u32_e32 v79, 0x2800, v4
	v_add_u32_e32 v80, 0x2a00, v4
	v_add_u32_e32 v81, 0x2c00, v4
	v_add_u32_e32 v82, 0x2e00, v4
	v_add_u32_e32 v83, 0x3000, v4
	v_add_u32_e32 v84, 0x3200, v4
	v_add_u32_e32 v85, 0x3400, v4
	v_add_u32_e32 v86, 0x3600, v4
	v_add_u32_e32 v87, 0x3800, v4
	v_add_u32_e32 v88, 0x3a00, v4
	v_add_u32_e32 v89, 0x3c00, v4
	v_add_u32_e32 v4, 0x3e00, v4
	global_load_dword v38, v38, s[10:11]
	s_nop 0
	global_load_dword v39, v39, s[10:11]
	s_nop 0
	global_load_dword v40, v40, s[10:11]
	s_nop 0
	global_load_dword v41, v41, s[10:11]
	s_nop 0
	global_load_dword v42, v42, s[10:11]
	s_nop 0
	global_load_dword v43, v43, s[10:11]
	s_nop 0
	global_load_dword v44, v44, s[10:11]
	s_nop 0
	global_load_dword v45, v45, s[10:11]
	s_nop 0
	global_load_dword v46, v46, s[10:11]
	s_nop 0
	global_load_dword v47, v47, s[10:11]
	s_nop 0
	global_load_dword v48, v48, s[10:11]
	s_nop 0
	global_load_dword v49, v49, s[10:11]
	s_nop 0
	global_load_dword v79, v79, s[10:11]
	s_nop 0
	global_load_dword v80, v80, s[10:11]
	s_nop 0
	global_load_dword v81, v81, s[10:11]
	s_nop 0
	global_load_dword v82, v82, s[10:11]
	s_nop 0
	global_load_dword v83, v83, s[10:11]
	s_nop 0
	global_load_dword v84, v84, s[10:11]
	s_nop 0
	global_load_dword v85, v85, s[10:11]
	s_nop 0
	global_load_dword v86, v86, s[10:11]
	s_nop 0
	global_load_dword v87, v87, s[10:11]
	s_nop 0
	global_load_dword v88, v88, s[10:11]
	s_nop 0
	global_load_dword v89, v89, s[10:11]
	s_nop 0
	global_load_dword v4, v4, s[10:11]
	v_add_u32_e32 v90, 0x1c00, v51
	s_lshl_b32 s44, s1, 1
	s_mov_b64 s[2:3], 0
	s_waitcnt vmcnt(30)
	ds_write2_b32 v51, v30, v31 offset1:66
	s_waitcnt vmcnt(28)
	ds_write2_b32 v51, v32, v33 offset0:132 offset1:198
	s_waitcnt vmcnt(26)
	ds_write2_b32 v72, v34, v35 offset0:8 offset1:74
	s_waitcnt vmcnt(24)
	ds_write2_b32 v72, v36, v37 offset0:140 offset1:206
	s_waitcnt vmcnt(22)
	ds_write2_b32 v73, v38, v39 offset0:16 offset1:82
	s_waitcnt vmcnt(20)
	ds_write2_b32 v73, v40, v41 offset0:148 offset1:214
	s_waitcnt vmcnt(18)
	ds_write2_b32 v74, v42, v43 offset0:24 offset1:90
	s_waitcnt vmcnt(16)
	ds_write2_b32 v74, v44, v45 offset0:156 offset1:222
	s_waitcnt vmcnt(14)
	ds_write2_b32 v75, v46, v47 offset0:32 offset1:98
	s_waitcnt vmcnt(12)
	ds_write2_b32 v75, v48, v49 offset0:164 offset1:230
	s_waitcnt vmcnt(10)
	ds_write2_b32 v76, v79, v80 offset0:40 offset1:106
	s_waitcnt vmcnt(8)
	ds_write2_b32 v76, v81, v82 offset0:172 offset1:238
	s_waitcnt vmcnt(6)
	ds_write2_b32 v77, v83, v84 offset0:48 offset1:114
	s_waitcnt vmcnt(4)
	ds_write2_b32 v77, v85, v86 offset0:180 offset1:246
	s_waitcnt vmcnt(2)
	ds_write2_b32 v90, v87, v88 offset0:56 offset1:122
	s_waitcnt vmcnt(0)
	ds_write2_b32 v90, v89, v4 offset0:188 offset1:254
	s_waitcnt lgkmcnt(0)
	ds_read2_b32 v[34:35], v53 offset0:33 offset1:41
	ds_read2_b32 v[36:37], v53 offset1:8
	ds_read2_b32 v[38:39], v53 offset0:66 offset1:74
	ds_read2_b32 v[40:41], v53 offset0:99 offset1:107
	ds_read2_b32 v[42:43], v53 offset0:132 offset1:140
	ds_read2_b32 v[44:45], v53 offset0:165 offset1:173
	ds_read2_b32 v[46:47], v53 offset0:198 offset1:206
	ds_read2_b32 v[48:49], v53 offset0:231 offset1:239
	v_or_b32_e32 v4, s0, v52
	v_lshl_add_u64 v[80:81], v[6:7], 0, s[44:45]
	v_lshlrev_b32_e32 v4, 8, v4
	s_waitcnt lgkmcnt(6)
	v_cvt_pk_bf16_f32 v30, v36, v34
	s_waitcnt lgkmcnt(4)
	v_cvt_pk_bf16_f32 v31, v38, v40
	s_waitcnt lgkmcnt(2)
	v_cvt_pk_bf16_f32 v32, v42, v44
	s_waitcnt lgkmcnt(0)
	v_cvt_pk_bf16_f32 v33, v46, v48
	v_lshl_add_u64 v[82:83], v[80:81], 0, v[4:5]
	global_store_dwordx4 v[82:83], v[30:33], off sc1
	v_or_b32_e32 v4, s0, v54
	v_lshlrev_b32_e32 v4, 8, v4
	v_cvt_pk_bf16_f32 v30, v37, v35
	v_cvt_pk_bf16_f32 v31, v39, v41
	v_cvt_pk_bf16_f32 v32, v43, v45
	v_cvt_pk_bf16_f32 v33, v47, v49
	ds_read2_b32 v[36:37], v53 offset0:49 offset1:57
	ds_read2_b32 v[38:39], v53 offset0:16 offset1:24
	ds_read2_b32 v[40:41], v53 offset0:82 offset1:90
	ds_read2_b32 v[42:43], v53 offset0:115 offset1:123
	ds_read2_b32 v[44:45], v53 offset0:148 offset1:156
	ds_read2_b32 v[46:47], v53 offset0:181 offset1:189
	ds_read2_b32 v[48:49], v53 offset0:214 offset1:222
	ds_read2_b32 v[82:83], v53 offset0:247 offset1:255
	v_lshl_add_u64 v[34:35], v[80:81], 0, v[4:5]
	v_or_b32_e32 v4, s0, v55
	v_lshlrev_b32_e32 v4, 8, v4
	global_store_dwordx4 v[34:35], v[30:33], off sc1
	v_lshl_add_u64 v[34:35], v[80:81], 0, v[4:5]
	v_or_b32_e32 v4, s0, v56
	s_waitcnt lgkmcnt(6)
	v_cvt_pk_bf16_f32 v30, v38, v36
	s_waitcnt lgkmcnt(4)
	v_cvt_pk_bf16_f32 v31, v40, v42
	s_waitcnt lgkmcnt(2)
	v_cvt_pk_bf16_f32 v32, v44, v46
	s_waitcnt lgkmcnt(0)
	v_cvt_pk_bf16_f32 v33, v48, v82
	v_lshlrev_b32_e32 v4, 8, v4
	global_store_dwordx4 v[34:35], v[30:33], off sc1
	v_lshl_add_u64 v[34:35], v[80:81], 0, v[4:5]
	s_nop 0
	v_cvt_pk_bf16_f32 v30, v39, v37
	v_cvt_pk_bf16_f32 v31, v41, v43
	v_cvt_pk_bf16_f32 v32, v45, v47
	v_cvt_pk_bf16_f32 v33, v49, v83
	global_store_dwordx4 v[34:35], v[30:33], off sc1
	s_waitcnt lgkmcnt(0)
; __device__ __forceinline__ unsigned cvt_pk_bf16(float lo, float hi) { f32x2 v = {lo, hi}; bf16x2_t b = __builtin_convertvector(v, bf16x2_t); return __builtin_bit_cast(unsigned, b); }
; #define LAS __attribute__((address_space(3)))
; #define LDS_WAIT() asm volatile("s_waitcnt lgkmcnt(0)" ::: "memory")
; template <int MODE> __device__ __forceinline__ void transpose_item(const float* W, int ldw, int K, int N, const float* ks, bf16_t* WT, LAS float* scr, int item, int lane) {
;     const int nblk = N / 32, kb = item / nblk, nb = item % nblk, k0 = 64 * kb, n0 = 32 * nb;
;     const int sc = src_col<MODE>(n0 + (lane & 31));
;     { float v[32];
; #pragma unroll
;         for (int i = 0; i < 32; ++i) { const int kk = 2 * i + (lane >> 5); v[i] = (sc >= 0) ? W[(size_t)(k0 + kk) * ldw + sc] : 0.f; }
; #pragma unroll
;         for (int i = 0; i < 32; ++i) { const int kk = 2 * i + (lane >> 5); float x = v[i]; if (ks) x *= ks[k0 + kk]; scr[kk * 33 + (lane & 31)] = x; } }
;     LDS_WAIT(); asm volatile("" ::: "memory");
;     const int c = lane & 7;
; #pragma unroll
;     for (int j = 0; j < 4; ++j) { const int n = (lane >> 3) + 8 * j; const LAS float* s = scr + (8 * c) * 33 + n;
;         u32x4 o; o.x = cvt_pk_bf16(s[0 * 33], s[1 * 33]); o.y = cvt_pk_bf16(s[2 * 33], s[3 * 33]); o.z = cvt_pk_bf16(s[4 * 33], s[5 * 33]); o.w = cvt_pk_bf16(s[6 * 33], s[7 * 33]);
;         *(u32x4*)(WT + (size_t)(n0 + n) * K + k0 + 8 * c) = o; }
;     LDS_WAIT(); asm volatile("" ::: "memory");
; }
; __device__ __forceinline__ void prep_phase(const Args& a, LAS unsigned char* lds, int vcu, int G, int wave, int lane) {
;     ...
;         if (r < I_C2) { transpose_item<0>(a.in[14], 64, 128, 64, nullptr, (bf16_t*)(ws + WS_CW2K), scr, r, lane); continue; } r -= I_C2;
.LBB0_24:
	s_andn2_b64 vcc, exec, s[2:3]
	s_cbranch_vccnz .LBB0_26
	s_add_i32 s0, s73, 0xd000
	s_and_b32 s1, s0, 0xffff
	s_add_i32 s2, s73, 0xcffe
	s_cmp_lt_u32 s1, 2
	s_cselect_b32 s0, s0, s2
	s_cmp_gt_u32 s1, 1
	s_cselect_b32 s1, 64, 0
	s_lshl_b32 s0, s0, 5
	s_and_b32 s0, s0, 0xffe0
	v_or_b32_e32 v30, s1, v2
	v_or_b32_e32 v4, s0, v1
	v_lshlrev_b32_e32 v30, 6, v30
	v_add_lshl_u32 v4, v4, v30, 2
	global_load_dword v30, v4, s[6:7]
	global_load_dword v31, v4, s[6:7] offset:512
	global_load_dword v32, v4, s[6:7] offset:1024
	global_load_dword v33, v4, s[6:7] offset:1536
	global_load_dword v34, v4, s[6:7] offset:2048
	global_load_dword v35, v4, s[6:7] offset:2560
	global_load_dword v36, v4, s[6:7] offset:3072
	global_load_dword v37, v4, s[6:7] offset:3584
	v_add_u32_e32 v38, 0x1000, v4
	v_add_u32_e32 v39, 0x1200, v4
	v_add_u32_e32 v40, 0x1400, v4
	v_add_u32_e32 v41, 0x1600, v4
	v_add_u32_e32 v42, 0x1800, v4
	v_add_u32_e32 v43, 0x1a00, v4
	v_add_u32_e32 v44, 0x1c00, v4
	v_add_u32_e32 v45, 0x1e00, v4
	v_add_u32_e32 v46, 0x2000, v4
	v_add_u32_e32 v47, 0x2200, v4
	v_add_u32_e32 v48, 0x2400, v4
	v_add_u32_e32 v49, 0x2600, v4
	v_add_u32_e32 v79, 0x2800, v4
	v_add_u32_e32 v80, 0x2a00, v4
	v_add_u32_e32 v81, 0x2c00, v4
	v_add_u32_e32 v82, 0x2e00, v4
	v_add_u32_e32 v83, 0x3000, v4
	v_add_u32_e32 v84, 0x3200, v4
	v_add_u32_e32 v85, 0x3400, v4
	v_add_u32_e32 v86, 0x3600, v4
	v_add_u32_e32 v87, 0x3800, v4
	v_add_u32_e32 v88, 0x3a00, v4
	v_add_u32_e32 v89, 0x3c00, v4
	v_add_u32_e32 v4, 0x3e00, v4
	global_load_dword v38, v38, s[6:7]
	s_nop 0
	global_load_dword v39, v39, s[6:7]
	s_nop 0
	global_load_dword v40, v40, s[6:7]
	s_nop 0
	global_load_dword v41, v41, s[6:7]
	s_nop 0
	global_load_dword v42, v42, s[6:7]
	s_nop 0
	global_load_dword v43, v43, s[6:7]
	s_nop 0
	global_load_dword v44, v44, s[6:7]
	s_nop 0
	global_load_dword v45, v45, s[6:7]
	s_nop 0
	global_load_dword v46, v46, s[6:7]
	s_nop 0
	global_load_dword v47, v47, s[6:7]
	s_nop 0
	global_load_dword v48, v48, s[6:7]
	s_nop 0
	global_load_dword v49, v49, s[6:7]
	s_nop 0
	global_load_dword v79, v79, s[6:7]
	s_nop 0
	global_load_dword v80, v80, s[6:7]
	s_nop 0
	global_load_dword v81, v81, s[6:7]
	s_nop 0
	global_load_dword v82, v82, s[6:7]
	s_nop 0
	global_load_dword v83, v83, s[6:7]
	s_nop 0
	global_load_dword v84, v84, s[6:7]
	s_nop 0
	global_load_dword v85, v85, s[6:7]
	s_nop 0
	global_load_dword v86, v86, s[6:7]
	s_nop 0
	global_load_dword v87, v87, s[6:7]
	s_nop 0
	global_load_dword v88, v88, s[6:7]
	s_nop 0
	global_load_dword v89, v89, s[6:7]
	s_nop 0
	global_load_dword v4, v4, s[6:7]
	v_add_u32_e32 v90, 0x1c00, v51
	s_lshl_b32 s44, s1, 1
	s_waitcnt vmcnt(30)
	ds_write2_b32 v51, v30, v31 offset1:66
	s_waitcnt vmcnt(28)
	ds_write2_b32 v51, v32, v33 offset0:132 offset1:198
	s_waitcnt vmcnt(26)
	ds_write2_b32 v72, v34, v35 offset0:8 offset1:74
	s_waitcnt vmcnt(24)
	ds_write2_b32 v72, v36, v37 offset0:140 offset1:206
	s_waitcnt vmcnt(22)
	ds_write2_b32 v73, v38, v39 offset0:16 offset1:82
	s_waitcnt vmcnt(20)
	ds_write2_b32 v73, v40, v41 offset0:148 offset1:214
	s_waitcnt vmcnt(18)
	ds_write2_b32 v74, v42, v43 offset0:24 offset1:90
	s_waitcnt vmcnt(16)
	ds_write2_b32 v74, v44, v45 offset0:156 offset1:222
	s_waitcnt vmcnt(14)
	ds_write2_b32 v75, v46, v47 offset0:32 offset1:98
	s_waitcnt vmcnt(12)
	ds_write2_b32 v75, v48, v49 offset0:164 offset1:230
	s_waitcnt vmcnt(10)
	ds_write2_b32 v76, v79, v80 offset0:40 offset1:106
	s_waitcnt vmcnt(8)
	ds_write2_b32 v76, v81, v82 offset0:172 offset1:238
	s_waitcnt vmcnt(6)
	ds_write2_b32 v77, v83, v84 offset0:48 offset1:114
	s_waitcnt vmcnt(4)
	ds_write2_b32 v77, v85, v86 offset0:180 offset1:246
	s_waitcnt vmcnt(2)
	ds_write2_b32 v90, v87, v88 offset0:56 offset1:122
	s_waitcnt vmcnt(0)
	ds_write2_b32 v90, v89, v4 offset0:188 offset1:254
	s_waitcnt lgkmcnt(0)
	ds_read2_b32 v[34:35], v53 offset0:33 offset1:41
	ds_read2_b32 v[36:37], v53 offset1:8
	ds_read2_b32 v[38:39], v53 offset0:66 offset1:74
	ds_read2_b32 v[40:41], v53 offset0:99 offset1:107
	ds_read2_b32 v[42:43], v53 offset0:132 offset1:140
	ds_read2_b32 v[44:45], v53 offset0:165 offset1:173
	ds_read2_b32 v[46:47], v53 offset0:198 offset1:206
	ds_read2_b32 v[48:49], v53 offset0:231 offset1:239
	v_or_b32_e32 v4, s0, v52
	v_lshl_add_u64 v[80:81], v[8:9], 0, s[44:45]
	v_lshlrev_b32_e32 v4, 8, v4
	s_waitcnt lgkmcnt(6)
	v_cvt_pk_bf16_f32 v30, v36, v34
	s_waitcnt lgkmcnt(4)
	v_cvt_pk_bf16_f32 v31, v38, v40
	s_waitcnt lgkmcnt(2)
	v_cvt_pk_bf16_f32 v32, v42, v44
	s_waitcnt lgkmcnt(0)
	v_cvt_pk_bf16_f32 v33, v46, v48
	v_lshl_add_u64 v[82:83], v[80:81], 0, v[4:5]
	global_store_dwordx4 v[82:83], v[30:33], off sc1
	v_or_b32_e32 v4, s0, v54
	v_lshlrev_b32_e32 v4, 8, v4
	v_cvt_pk_bf16_f32 v30, v37, v35
	v_cvt_pk_bf16_f32 v31, v39, v41
	v_cvt_pk_bf16_f32 v32, v43, v45
	v_cvt_pk_bf16_f32 v33, v47, v49
	ds_read2_b32 v[36:37], v53 offset0:49 offset1:57
	ds_read2_b32 v[38:39], v53 offset0:16 offset1:24
	ds_read2_b32 v[40:41], v53 offset0:82 offset1:90
	ds_read2_b32 v[42:43], v53 offset0:115 offset1:123
	ds_read2_b32 v[44:45], v53 offset0:148 offset1:156
	ds_read2_b32 v[46:47], v53 offset0:181 offset1:189
	ds_read2_b32 v[48:49], v53 offset0:214 offset1:222
	ds_read2_b32 v[82:83], v53 offset0:247 offset1:255
	v_lshl_add_u64 v[34:35], v[80:81], 0, v[4:5]
	v_or_b32_e32 v4, s0, v55
	v_lshlrev_b32_e32 v4, 8, v4
	global_store_dwordx4 v[34:35], v[30:33], off sc1
	v_lshl_add_u64 v[34:35], v[80:81], 0, v[4:5]
	v_or_b32_e32 v4, s0, v56
	s_waitcnt lgkmcnt(6)
	v_cvt_pk_bf16_f32 v30, v38, v36
	s_waitcnt lgkmcnt(4)
	v_cvt_pk_bf16_f32 v31, v40, v42
	s_waitcnt lgkmcnt(2)
	v_cvt_pk_bf16_f32 v32, v44, v46
	s_waitcnt lgkmcnt(0)
	v_cvt_pk_bf16_f32 v33, v48, v82
	v_lshlrev_b32_e32 v4, 8, v4
	global_store_dwordx4 v[34:35], v[30:33], off sc1
	v_lshl_add_u64 v[34:35], v[80:81], 0, v[4:5]
	s_nop 0
	v_cvt_pk_bf16_f32 v30, v39, v37
	v_cvt_pk_bf16_f32 v31, v41, v43
	v_cvt_pk_bf16_f32 v32, v45, v47
	v_cvt_pk_bf16_f32 v33, v49, v83
	global_store_dwordx4 v[34:35], v[30:33], off sc1
	s_waitcnt lgkmcnt(0)

; __device__ __forceinline__ unsigned cvt_pk_bf16(float lo, float hi) { f32x2 v = {lo, hi}; bf16x2_t b = __builtin_convertvector(v, bf16x2_t); return __builtin_bit_cast(unsigned, b); }
; #define LAS __attribute__((address_space(3)))
; #define LDS_WAIT() asm volatile("s_waitcnt lgkmcnt(0)" ::: "memory")
; template <int MODE> __device__ __forceinline__ void transpose_item(const float* W, int ldw, int K, int N, const float* ks, bf16_t* WT, LAS float* scr, int item, int lane) {
;     const int nblk = N / 32, kb = item / nblk, nb = item % nblk, k0 = 64 * kb, n0 = 32 * nb;
;     const int sc = src_col<MODE>(n0 + (lane & 31));
;     { float v[32];
; #pragma unroll
;         for (int i = 0; i < 32; ++i) { const int kk = 2 * i + (lane >> 5); v[i] = (sc >= 0) ? W[(size_t)(k0 + kk) * ldw + sc] : 0.f; }
; #pragma unroll
;         for (int i = 0; i < 32; ++i) { const int kk = 2 * i + (lane >> 5); float x = v[i]; if (ks) x *= ks[k0 + kk]; scr[kk * 33 + (lane & 31)] = x; } }
;     LDS_WAIT(); asm volatile("" ::: "memory");
;     const int c = lane & 7;
; #pragma unroll
;     for (int j = 0; j < 4; ++j) { const int n = (lane >> 3) + 8 * j; const LAS float* s = scr + (8 * c) * 33 + n;
;         u32x4 o; o.x = cvt_pk_bf16(s[0 * 33], s[1 * 33]); o.y = cvt_pk_bf16(s[2 * 33], s[3 * 33]); o.z = cvt_pk_bf16(s[4 * 33], s[5 * 33]); o.w = cvt_pk_bf16(s[6 * 33], s[7 * 33]);
;         *(u32x4*)(WT + (size_t)(n0 + n) * K + k0 + 8 * c) = o; }
;     LDS_WAIT(); asm volatile("" ::: "memory");
; }
; __device__ __forceinline__ void prep_phase(const Args& a, LAS unsigned char* lds, int vcu, int G, int wave, int lane) {
;     ...
;         if (r < I_C1) { transpose_item<0>(a.in[15], 128, 2048, 128, nullptr, (bf16_t*)(ws + WS_CW1V), scr, r, lane); continue; } r -= I_C1;
.LBB0_27:
	s_andn2_b64 vcc, exec, s[2:3]
	s_cbranch_vccnz .LBB0_29
	s_and_b32 s1, s63, 0xfc0
	v_bitop3_b32 v4, s1, v2, v78 bitop3:0xde
	s_and_b32 s0, s61, 0x60
	v_lshlrev_b32_e32 v4, 7, v4
	v_or3_b32 v4, v4, v1, s0
	v_lshlrev_b32_e32 v4, 2, v4
	v_lshl_add_u64 v[30:31], s[8:9], 0, v[4:5]
	v_add_co_u32_e32 v32, vcc, 0x1000, v30
	global_load_dword v36, v4, s[8:9]
	global_load_dword v37, v4, s[8:9] offset:1024
	global_load_dword v38, v4, s[8:9] offset:2048
	s_nop 0
	global_load_dword v4, v4, s[8:9] offset:3072
	v_addc_co_u32_e32 v33, vcc, 0, v31, vcc
	v_add_co_u32_e32 v34, vcc, 0x2000, v30
	s_xor_b32 s1, s1, 0x800
	s_nop 0
	v_addc_co_u32_e32 v35, vcc, 0, v31, vcc
	global_load_dword v39, v[32:33], off
	global_load_dword v40, v[32:33], off offset:1024
	global_load_dword v41, v[32:33], off offset:2048
	global_load_dword v42, v[32:33], off offset:3072
	global_load_dword v43, v[34:35], off
	global_load_dword v44, v[34:35], off offset:1024
	global_load_dword v45, v[34:35], off offset:2048
	global_load_dword v46, v[34:35], off offset:3072
	v_add_co_u32_e32 v32, vcc, 0x3000, v30
	s_lshl_b32 s44, s1, 1
	s_nop 0
	v_addc_co_u32_e32 v33, vcc, 0, v31, vcc
	v_add_co_u32_e32 v34, vcc, 0x4000, v30
	s_nop 1
	v_addc_co_u32_e32 v35, vcc, 0, v31, vcc
	global_load_dword v47, v[32:33], off
	global_load_dword v48, v[32:33], off offset:1024
	global_load_dword v49, v[32:33], off offset:2048
	global_load_dword v79, v[32:33], off offset:3072
	global_load_dword v80, v[34:35], off
	global_load_dword v81, v[34:35], off offset:1024
	global_load_dword v82, v[34:35], off offset:2048
	global_load_dword v83, v[34:35], off offset:3072
	v_add_co_u32_e32 v32, vcc, 0x5000, v30
	s_nop 1
	v_addc_co_u32_e32 v33, vcc, 0, v31, vcc
	v_add_co_u32_e32 v34, vcc, 0x6000, v30
	s_nop 1
	v_addc_co_u32_e32 v35, vcc, 0, v31, vcc
	v_add_co_u32_e32 v30, vcc, 0x7000, v30
	global_load_dword v84, v[32:33], off
	global_load_dword v85, v[32:33], off offset:1024
	global_load_dword v86, v[32:33], off offset:2048
	s_nop 0
	global_load_dword v32, v[32:33], off offset:3072
	s_nop 0
	global_load_dword v33, v[34:35], off
	global_load_dword v87, v[34:35], off offset:1024
	global_load_dword v88, v[34:35], off offset:2048
	s_nop 0
	global_load_dword v34, v[34:35], off offset:3072
	v_addc_co_u32_e32 v31, vcc, 0, v31, vcc
	global_load_dword v35, v[30:31], off
	global_load_dword v89, v[30:31], off offset:1024
	global_load_dword v90, v[30:31], off offset:2048
	s_nop 0
	global_load_dword v30, v[30:31], off offset:3072
	v_add_u32_e32 v31, 0x1c00, v51
	s_waitcnt vmcnt(30)
	ds_write2_b32 v51, v36, v37 offset1:66
	s_waitcnt vmcnt(28)
	ds_write2_b32 v51, v38, v4 offset0:132 offset1:198
	s_waitcnt vmcnt(26)
	ds_write2_b32 v72, v39, v40 offset0:8 offset1:74
	s_waitcnt vmcnt(24)
	ds_write2_b32 v72, v41, v42 offset0:140 offset1:206
	s_waitcnt vmcnt(22)
	ds_write2_b32 v73, v43, v44 offset0:16 offset1:82
	s_waitcnt vmcnt(20)
	ds_write2_b32 v73, v45, v46 offset0:148 offset1:214
	s_waitcnt vmcnt(18)
	ds_write2_b32 v74, v47, v48 offset0:24 offset1:90
	s_waitcnt vmcnt(16)
	ds_write2_b32 v74, v49, v79 offset0:156 offset1:222
	s_waitcnt vmcnt(14)
	ds_write2_b32 v75, v80, v81 offset0:32 offset1:98
	s_waitcnt vmcnt(12)
	ds_write2_b32 v75, v82, v83 offset0:164 offset1:230
	s_waitcnt vmcnt(10)
	ds_write2_b32 v76, v84, v85 offset0:40 offset1:106
	s_waitcnt vmcnt(8)
	ds_write2_b32 v76, v86, v32 offset0:172 offset1:238
	s_waitcnt vmcnt(6)
	ds_write2_b32 v77, v33, v87 offset0:48 offset1:114
	s_waitcnt vmcnt(4)
	ds_write2_b32 v77, v88, v34 offset0:180 offset1:246
	s_waitcnt vmcnt(2)
	ds_write2_b32 v31, v35, v89 offset0:56 offset1:122
	s_waitcnt vmcnt(0)
	ds_write2_b32 v31, v90, v30 offset0:188 offset1:254
	s_waitcnt lgkmcnt(0)
	ds_read2_b32 v[34:35], v53 offset0:33 offset1:41
	ds_read2_b32 v[36:37], v53 offset1:8
	ds_read2_b32 v[38:39], v53 offset0:66 offset1:74
	ds_read2_b32 v[40:41], v53 offset0:99 offset1:107
	ds_read2_b32 v[42:43], v53 offset0:132 offset1:140
	ds_read2_b32 v[44:45], v53 offset0:165 offset1:173
	ds_read2_b32 v[46:47], v53 offset0:198 offset1:206
	ds_read2_b32 v[48:49], v53 offset0:231 offset1:239
	v_or_b32_e32 v4, s0, v52
	v_lshl_add_u64 v[80:81], v[10:11], 0, s[44:45]
	v_lshlrev_b32_e32 v4, 12, v4
	s_waitcnt lgkmcnt(6)
	v_cvt_pk_bf16_f32 v30, v36, v34
	s_waitcnt lgkmcnt(4)
	v_cvt_pk_bf16_f32 v31, v38, v40
	s_waitcnt lgkmcnt(2)
	v_cvt_pk_bf16_f32 v32, v42, v44
	s_waitcnt lgkmcnt(0)
	v_cvt_pk_bf16_f32 v33, v46, v48
	v_lshl_add_u64 v[82:83], v[80:81], 0, v[4:5]
	global_store_dwordx4 v[82:83], v[30:33], off sc1
	v_or_b32_e32 v4, s0, v54
	v_lshlrev_b32_e32 v4, 12, v4
	v_cvt_pk_bf16_f32 v30, v37, v35
	v_cvt_pk_bf16_f32 v31, v39, v41
	v_cvt_pk_bf16_f32 v32, v43, v45
	v_cvt_pk_bf16_f32 v33, v47, v49
	ds_read2_b32 v[36:37], v53 offset0:49 offset1:57
	ds_read2_b32 v[38:39], v53 offset0:16 offset1:24
	ds_read2_b32 v[40:41], v53 offset0:82 offset1:90
	ds_read2_b32 v[42:43], v53 offset0:115 offset1:123
	ds_read2_b32 v[44:45], v53 offset0:148 offset1:156
	ds_read2_b32 v[46:47], v53 offset0:181 offset1:189
	ds_read2_b32 v[48:49], v53 offset0:214 offset1:222
	ds_read2_b32 v[82:83], v53 offset0:247 offset1:255
	v_lshl_add_u64 v[34:35], v[80:81], 0, v[4:5]
	v_or_b32_e32 v4, s0, v55
	v_lshlrev_b32_e32 v4, 12, v4
	global_store_dwordx4 v[34:35], v[30:33], off sc1
	v_lshl_add_u64 v[34:35], v[80:81], 0, v[4:5]
	v_or_b32_e32 v4, s0, v56
	s_waitcnt lgkmcnt(6)
	v_cvt_pk_bf16_f32 v30, v38, v36
	s_waitcnt lgkmcnt(4)
	v_cvt_pk_bf16_f32 v31, v40, v42
	s_waitcnt lgkmcnt(2)
	v_cvt_pk_bf16_f32 v32, v44, v46
	s_waitcnt lgkmcnt(0)
	v_cvt_pk_bf16_f32 v33, v48, v82
	v_lshlrev_b32_e32 v4, 12, v4
	global_store_dwordx4 v[34:35], v[30:33], off sc1
	v_lshl_add_u64 v[34:35], v[80:81], 0, v[4:5]
	s_nop 0
	v_cvt_pk_bf16_f32 v30, v39, v37
	v_cvt_pk_bf16_f32 v31, v41, v43
	v_cvt_pk_bf16_f32 v32, v45, v47
	v_cvt_pk_bf16_f32 v33, v49, v83
	global_store_dwordx4 v[34:35], v[30:33], off sc1
	s_waitcnt lgkmcnt(0)

; __device__ __forceinline__ unsigned cvt_pk_bf16(float lo, float hi) { f32x2 v = {lo, hi}; bf16x2_t b = __builtin_convertvector(v, bf16x2_t); return __builtin_bit_cast(unsigned, b); }
; #define LAS __attribute__((address_space(3)))
; #define LDS_WAIT() asm volatile("s_waitcnt lgkmcnt(0)" ::: "memory")
; template <int MODE> __device__ __forceinline__ void transpose_item(const float* W, int ldw, int K, int N, const float* ks, bf16_t* WT, LAS float* scr, int item, int lane) {
;     const int nblk = N / 32, kb = item / nblk, nb = item % nblk, k0 = 64 * kb, n0 = 32 * nb;
;     const int sc = src_col<MODE>(n0 + (lane & 31));
;     { float v[32];
; #pragma unroll
;         for (int i = 0; i < 32; ++i) { const int kk = 2 * i + (lane >> 5); v[i] = (sc >= 0) ? W[(size_t)(k0 + kk) * ldw + sc] : 0.f; }
; #pragma unroll
;         for (int i = 0; i < 32; ++i) { const int kk = 2 * i + (lane >> 5); float x = v[i]; if (ks) x *= ks[k0 + kk]; scr[kk * 33 + (lane & 31)] = x; } }
;     LDS_WAIT(); asm volatile("" ::: "memory");
;     const int c = lane & 7;
; #pragma unroll
;     for (int j = 0; j < 4; ++j) { const int n = (lane >> 3) + 8 * j; const LAS float* s = scr + (8 * c) * 33 + n;
;         u32x4 o; o.x = cvt_pk_bf16(s[0 * 33], s[1 * 33]); o.y = cvt_pk_bf16(s[2 * 33], s[3 * 33]); o.z = cvt_pk_bf16(s[4 * 33], s[5 * 33]); o.w = cvt_pk_bf16(s[6 * 33], s[7 * 33]);
;         *(u32x4*)(WT + (size_t)(n0 + n) * K + k0 + 8 * c) = o; }
;     LDS_WAIT(); asm volatile("" ::: "memory");
; }
.LBB0_30:
	s_andn2_b64 vcc, exec, s[2:3]
	s_cbranch_vccnz .LBB0_32
	s_and_b32 s1, s63, 0xfc0
	v_or_b32_e32 v4, s1, v2
	s_and_b32 s0, s61, 0x60
	v_lshlrev_b32_e32 v4, 7, v4
	v_or3_b32 v4, v4, v1, s0
	v_lshlrev_b32_e32 v4, 2, v4
	v_lshl_add_u64 v[30:31], s[4:5], 0, v[4:5]
	v_add_co_u32_e32 v32, vcc, 0x1000, v30
	global_load_dword v36, v4, s[4:5]
	global_load_dword v37, v4, s[4:5] offset:1024
	global_load_dword v38, v4, s[4:5] offset:2048
	s_nop 0
	global_load_dword v4, v4, s[4:5] offset:3072
	v_addc_co_u32_e32 v33, vcc, 0, v31, vcc
	v_add_co_u32_e32 v34, vcc, 0x2000, v30
	s_lshl_b32 s44, s1, 1
	s_nop 0
	v_addc_co_u32_e32 v35, vcc, 0, v31, vcc
	global_load_dword v39, v[32:33], off
	global_load_dword v40, v[32:33], off offset:1024
	global_load_dword v41, v[32:33], off offset:2048
	global_load_dword v42, v[32:33], off offset:3072
	global_load_dword v43, v[34:35], off
	global_load_dword v44, v[34:35], off offset:1024
	global_load_dword v45, v[34:35], off offset:2048
	global_load_dword v46, v[34:35], off offset:3072
	v_add_co_u32_e32 v32, vcc, 0x3000, v30
	s_nop 1
	v_addc_co_u32_e32 v33, vcc, 0, v31, vcc
	v_add_co_u32_e32 v34, vcc, 0x4000, v30
	s_nop 1
	v_addc_co_u32_e32 v35, vcc, 0, v31, vcc
	global_load_dword v47, v[32:33], off
	global_load_dword v48, v[32:33], off offset:1024
	global_load_dword v49, v[32:33], off offset:2048
	global_load_dword v79, v[32:33], off offset:3072
	global_load_dword v80, v[34:35], off
	global_load_dword v81, v[34:35], off offset:1024
	global_load_dword v82, v[34:35], off offset:2048
	global_load_dword v83, v[34:35], off offset:3072
	v_add_co_u32_e32 v32, vcc, 0x5000, v30
	s_nop 1
	v_addc_co_u32_e32 v33, vcc, 0, v31, vcc
	v_add_co_u32_e32 v34, vcc, 0x6000, v30
	s_nop 1
	v_addc_co_u32_e32 v35, vcc, 0, v31, vcc
	v_add_co_u32_e32 v30, vcc, 0x7000, v30
	global_load_dword v84, v[32:33], off
	global_load_dword v85, v[32:33], off offset:1024
	global_load_dword v86, v[32:33], off offset:2048
	s_nop 0
	global_load_dword v32, v[32:33], off offset:3072
	s_nop 0
	global_load_dword v33, v[34:35], off
	global_load_dword v87, v[34:35], off offset:1024
	global_load_dword v88, v[34:35], off offset:2048
	s_nop 0
	global_load_dword v34, v[34:35], off offset:3072
	v_addc_co_u32_e32 v31, vcc, 0, v31, vcc
	global_load_dword v35, v[30:31], off
	global_load_dword v89, v[30:31], off offset:1024
	global_load_dword v90, v[30:31], off offset:2048
	s_nop 0
	global_load_dword v30, v[30:31], off offset:3072
	v_add_u32_e32 v31, 0x1c00, v51
	s_waitcnt vmcnt(30)
	ds_write2_b32 v51, v36, v37 offset1:66
	s_waitcnt vmcnt(28)
	ds_write2_b32 v51, v38, v4 offset0:132 offset1:198
	s_waitcnt vmcnt(26)
	ds_write2_b32 v72, v39, v40 offset0:8 offset1:74
	s_waitcnt vmcnt(24)
	ds_write2_b32 v72, v41, v42 offset0:140 offset1:206
	s_waitcnt vmcnt(22)
	ds_write2_b32 v73, v43, v44 offset0:16 offset1:82
	s_waitcnt vmcnt(20)
	ds_write2_b32 v73, v45, v46 offset0:148 offset1:214
	s_waitcnt vmcnt(18)
	ds_write2_b32 v74, v47, v48 offset0:24 offset1:90
	s_waitcnt vmcnt(16)
	ds_write2_b32 v74, v49, v79 offset0:156 offset1:222
	s_waitcnt vmcnt(14)
	ds_write2_b32 v75, v80, v81 offset0:32 offset1:98
	s_waitcnt vmcnt(12)
	ds_write2_b32 v75, v82, v83 offset0:164 offset1:230
	s_waitcnt vmcnt(10)
	ds_write2_b32 v76, v84, v85 offset0:40 offset1:106
	s_waitcnt vmcnt(8)
	ds_write2_b32 v76, v86, v32 offset0:172 offset1:238
	s_waitcnt vmcnt(6)
	ds_write2_b32 v77, v33, v87 offset0:48 offset1:114
	s_waitcnt vmcnt(4)
	ds_write2_b32 v77, v88, v34 offset0:180 offset1:246
	s_waitcnt vmcnt(2)
	ds_write2_b32 v31, v35, v89 offset0:56 offset1:122
	s_waitcnt vmcnt(0)
	ds_write2_b32 v31, v90, v30 offset0:188 offset1:254
	s_waitcnt lgkmcnt(0)
	ds_read2_b32 v[34:35], v53 offset0:33 offset1:41
	ds_read2_b32 v[36:37], v53 offset1:8
	ds_read2_b32 v[38:39], v53 offset0:66 offset1:74
	ds_read2_b32 v[40:41], v53 offset0:99 offset1:107
	ds_read2_b32 v[42:43], v53 offset0:132 offset1:140
	ds_read2_b32 v[44:45], v53 offset0:165 offset1:173
	ds_read2_b32 v[46:47], v53 offset0:198 offset1:206
	ds_read2_b32 v[48:49], v53 offset0:231 offset1:239
	v_or_b32_e32 v4, s0, v52
	v_lshl_add_u64 v[80:81], v[12:13], 0, s[44:45]
	v_lshlrev_b32_e32 v4, 12, v4
	s_waitcnt lgkmcnt(6)
	v_cvt_pk_bf16_f32 v30, v36, v34
	s_waitcnt lgkmcnt(4)
	v_cvt_pk_bf16_f32 v31, v38, v40
	s_waitcnt lgkmcnt(2)
	v_cvt_pk_bf16_f32 v32, v42, v44
	s_waitcnt lgkmcnt(0)
	v_cvt_pk_bf16_f32 v33, v46, v48
	v_lshl_add_u64 v[82:83], v[80:81], 0, v[4:5]
	global_store_dwordx4 v[82:83], v[30:33], off sc1
	v_or_b32_e32 v4, s0, v54
	v_lshlrev_b32_e32 v4, 12, v4
	v_cvt_pk_bf16_f32 v30, v37, v35
	v_cvt_pk_bf16_f32 v31, v39, v41
	v_cvt_pk_bf16_f32 v32, v43, v45
	v_cvt_pk_bf16_f32 v33, v47, v49
	ds_read2_b32 v[36:37], v53 offset0:49 offset1:57
	ds_read2_b32 v[38:39], v53 offset0:16 offset1:24
	ds_read2_b32 v[40:41], v53 offset0:82 offset1:90
	ds_read2_b32 v[42:43], v53 offset0:115 offset1:123
	ds_read2_b32 v[44:45], v53 offset0:148 offset1:156
	ds_read2_b32 v[46:47], v53 offset0:181 offset1:189
	ds_read2_b32 v[48:49], v53 offset0:214 offset1:222
	ds_read2_b32 v[82:83], v53 offset0:247 offset1:255
	v_lshl_add_u64 v[34:35], v[80:81], 0, v[4:5]
	v_or_b32_e32 v4, s0, v55
	v_lshlrev_b32_e32 v4, 12, v4
	global_store_dwordx4 v[34:35], v[30:33], off sc1
	v_lshl_add_u64 v[34:35], v[80:81], 0, v[4:5]
	v_or_b32_e32 v4, s0, v56
	s_waitcnt lgkmcnt(6)
	v_cvt_pk_bf16_f32 v30, v38, v36
	s_waitcnt lgkmcnt(4)
	v_cvt_pk_bf16_f32 v31, v40, v42
	s_waitcnt lgkmcnt(2)
	v_cvt_pk_bf16_f32 v32, v44, v46
	s_waitcnt lgkmcnt(0)
	v_cvt_pk_bf16_f32 v33, v48, v82
	v_lshlrev_b32_e32 v4, 12, v4
	global_store_dwordx4 v[34:35], v[30:33], off sc1
	v_lshl_add_u64 v[34:35], v[80:81], 0, v[4:5]
	s_nop 0
	v_cvt_pk_bf16_f32 v30, v39, v37
	v_cvt_pk_bf16_f32 v31, v41, v43
	v_cvt_pk_bf16_f32 v32, v45, v47
	v_cvt_pk_bf16_f32 v33, v49, v83
	global_store_dwordx4 v[34:35], v[30:33], off sc1
	s_waitcnt lgkmcnt(0)

; template <int MODE> __device__ __forceinline__ void transpose_item(const float* W, int ldw, int K, int N, const float* ks, bf16_t* WT, LAS float* scr, int item, int lane) {
;     ...
;     { float v[32];
; #pragma unroll
;         for (int i = 0; i < 32; ++i) { const int kk = 2 * i + (lane >> 5); v[i] = (sc >= 0) ? W[(size_t)(k0 + kk) * ldw + sc] : 0.f; }
.LBB0_33:
	s_andn2_b64 vcc, exec, s[2:3]
	s_cbranch_vccnz .LBB0_35
	s_add_i32 s0, s65, 0x1a600
	s_and_b32 s1, s0, 0x1ffc0
	v_or_b32_e32 v4, s1, v2
	s_and_b32 s0, s61, 0x3e0
	v_lshlrev_b32_e32 v4, 10, v4
	v_or3_b32 v4, v4, v1, s0
	v_lshlrev_b32_e32 v4, 2, v4
	v_lshl_add_u64 v[30:31], s[16:17], 0, v[4:5]
	v_add_co_u32_e32 v32, vcc, 0x2000, v30
	global_load_dword v4, v4, s[16:17]
	s_nop 0
	v_addc_co_u32_e32 v33, vcc, 0, v31, vcc
	v_add_co_u32_e32 v34, vcc, 0x4000, v30
	s_lshl_b32 s44, s1, 1
	s_nop 0
	v_addc_co_u32_e32 v35, vcc, 0, v31, vcc
	v_add_co_u32_e32 v36, vcc, 0x6000, v30
	s_nop 1
	v_addc_co_u32_e32 v37, vcc, 0, v31, vcc
	v_add_co_u32_e32 v38, vcc, 0x8000, v30
	s_nop 1
	v_addc_co_u32_e32 v39, vcc, 0, v31, vcc
	v_add_co_u32_e32 v40, vcc, 0xa000, v30
	s_nop 1
	v_addc_co_u32_e32 v41, vcc, 0, v31, vcc
	v_add_co_u32_e32 v42, vcc, 0xc000, v30
	s_nop 1
	v_addc_co_u32_e32 v43, vcc, 0, v31, vcc
	v_add_co_u32_e32 v44, vcc, 0xe000, v30
	s_nop 1
	v_addc_co_u32_e32 v45, vcc, 0, v31, vcc
	v_add_co_u32_e32 v46, vcc, 0x10000, v30
	s_nop 1
	v_addc_co_u32_e32 v47, vcc, 0, v31, vcc
	global_load_dword v48, v[32:33], off
	global_load_dword v49, v[34:35], off
	global_load_dword v79, v[36:37], off
	global_load_dword v80, v[38:39], off
	global_load_dword v81, v[40:41], off
	global_load_dword v82, v[42:43], off
	global_load_dword v83, v[44:45], off
	global_load_dword v84, v[46:47], off
	v_add_co_u32_e32 v32, vcc, 0x12000, v30
	s_nop 1
	v_addc_co_u32_e32 v33, vcc, 0, v31, vcc
	v_add_co_u32_e32 v34, vcc, 0x14000, v30
	s_nop 1
	v_addc_co_u32_e32 v35, vcc, 0, v31, vcc
	v_add_co_u32_e32 v36, vcc, 0x16000, v30
	s_nop 1
	v_addc_co_u32_e32 v37, vcc, 0, v31, vcc
	v_add_co_u32_e32 v38, vcc, 0x18000, v30
	s_nop 1
	v_addc_co_u32_e32 v39, vcc, 0, v31, vcc
	v_add_co_u32_e32 v40, vcc, 0x1a000, v30
	s_nop 1
	v_addc_co_u32_e32 v41, vcc, 0, v31, vcc
	v_add_co_u32_e32 v42, vcc, 0x1c000, v30
	s_nop 1
	v_addc_co_u32_e32 v43, vcc, 0, v31, vcc
	v_add_co_u32_e32 v44, vcc, 0x1e000, v30
	s_nop 1
	v_addc_co_u32_e32 v45, vcc, 0, v31, vcc
	v_add_co_u32_e32 v46, vcc, 0x20000, v30
	s_nop 1
	v_addc_co_u32_e32 v47, vcc, 0, v31, vcc
	global_load_dword v85, v[32:33], off
	global_load_dword v86, v[34:35], off
	global_load_dword v87, v[36:37], off
	global_load_dword v88, v[38:39], off
	global_load_dword v89, v[40:41], off
	global_load_dword v90, v[42:43], off
	global_load_dword v91, v[44:45], off
	global_load_dword v92, v[46:47], off
	v_add_co_u32_e32 v32, vcc, 0x22000, v30
	s_nop 1
	v_addc_co_u32_e32 v33, vcc, 0, v31, vcc
	v_add_co_u32_e32 v34, vcc, 0x24000, v30
	s_nop 1
	v_addc_co_u32_e32 v35, vcc, 0, v31, vcc
	v_add_co_u32_e32 v36, vcc, 0x26000, v30
	s_nop 1
	v_addc_co_u32_e32 v37, vcc, 0, v31, vcc
	v_add_co_u32_e32 v38, vcc, 0x28000, v30
	s_nop 1
	v_addc_co_u32_e32 v39, vcc, 0, v31, vcc
	v_add_co_u32_e32 v40, vcc, 0x2a000, v30
	s_nop 1
	v_addc_co_u32_e32 v41, vcc, 0, v31, vcc
	v_add_co_u32_e32 v42, vcc, 0x2c000, v30
	s_nop 1
	v_addc_co_u32_e32 v43, vcc, 0, v31, vcc
	v_add_co_u32_e32 v44, vcc, 0x2e000, v30
	s_nop 1
	v_addc_co_u32_e32 v45, vcc, 0, v31, vcc
	v_add_co_u32_e32 v46, vcc, 0x30000, v30
	s_nop 1
	v_addc_co_u32_e32 v47, vcc, 0, v31, vcc
	global_load_dword v93, v[32:33], off
	global_load_dword v94, v[34:35], off
	global_load_dword v95, v[36:37], off
	global_load_dword v96, v[38:39], off
	global_load_dword v97, v[40:41], off
	global_load_dword v98, v[42:43], off
	s_nop 0
	global_load_dword v44, v[44:45], off
	s_nop 0
	global_load_dword v45, v[46:47], off
	v_add_co_u32_e32 v32, vcc, 0x32000, v30
	s_nop 1
	v_addc_co_u32_e32 v33, vcc, 0, v31, vcc
	v_add_co_u32_e32 v34, vcc, 0x34000, v30
	s_nop 1
	v_addc_co_u32_e32 v35, vcc, 0, v31, vcc
	v_add_co_u32_e32 v36, vcc, 0x36000, v30
	s_nop 1
	v_addc_co_u32_e32 v37, vcc, 0, v31, vcc
	v_add_co_u32_e32 v38, vcc, 0x38000, v30
	s_nop 1
	v_addc_co_u32_e32 v39, vcc, 0, v31, vcc
	v_add_co_u32_e32 v40, vcc, 0x3a000, v30
	s_nop 1
	v_addc_co_u32_e32 v41, vcc, 0, v31, vcc
	v_add_co_u32_e32 v42, vcc, 0x3c000, v30
	s_nop 1
	v_addc_co_u32_e32 v43, vcc, 0, v31, vcc
	v_add_co_u32_e32 v30, vcc, 0x3e000, v30
	s_nop 1
	v_addc_co_u32_e32 v31, vcc, 0, v31, vcc
	global_load_dword v32, v[32:33], off
	s_nop 0
	global_load_dword v33, v[34:35], off
	s_nop 0
	global_load_dword v34, v[36:37], off
	global_load_dword v35, v[38:39], off
	s_nop 0
	global_load_dword v36, v[40:41], off
	global_load_dword v37, v[42:43], off
	s_nop 0
	global_load_dword v30, v[30:31], off
	s_waitcnt vmcnt(30)
; __device__ __forceinline__ unsigned cvt_pk_bf16(float lo, float hi) { f32x2 v = {lo, hi}; bf16x2_t b = __builtin_convertvector(v, bf16x2_t); return __builtin_bit_cast(unsigned, b); }
; #define LAS __attribute__((address_space(3)))
; #define LDS_WAIT() asm volatile("s_waitcnt lgkmcnt(0)" ::: "memory")
; template <int MODE> __device__ __forceinline__ void transpose_item(const float* W, int ldw, int K, int N, const float* ks, bf16_t* WT, LAS float* scr, int item, int lane) {
;     ...
; #pragma unroll
;         for (int i = 0; i < 32; ++i) { const int kk = 2 * i + (lane >> 5); float x = v[i]; if (ks) x *= ks[k0 + kk]; scr[kk * 33 + (lane & 31)] = x; } }
;     LDS_WAIT(); asm volatile("" ::: "memory");
;     const int c = lane & 7;
; #pragma unroll
;     for (int j = 0; j < 4; ++j) { const int n = (lane >> 3) + 8 * j; const LAS float* s = scr + (8 * c) * 33 + n;
;         u32x4 o; o.x = cvt_pk_bf16(s[0 * 33], s[1 * 33]); o.y = cvt_pk_bf16(s[2 * 33], s[3 * 33]); o.z = cvt_pk_bf16(s[4 * 33], s[5 * 33]); o.w = cvt_pk_bf16(s[6 * 33], s[7 * 33]);
;         *(u32x4*)(WT + (size_t)(n0 + n) * K + k0 + 8 * c) = o; }
;     LDS_WAIT(); asm volatile("" ::: "memory");
	ds_write2_b32 v51, v4, v48 offset1:66
	s_waitcnt vmcnt(28)
	ds_write2_b32 v51, v49, v79 offset0:132 offset1:198
	s_waitcnt vmcnt(26)
	ds_write2_b32 v72, v80, v81 offset0:8 offset1:74
	s_waitcnt vmcnt(24)
	ds_write2_b32 v72, v82, v83 offset0:140 offset1:206
	s_waitcnt vmcnt(22)
	ds_write2_b32 v73, v84, v85 offset0:16 offset1:82
	s_waitcnt vmcnt(20)
	ds_write2_b32 v73, v86, v87 offset0:148 offset1:214
	s_waitcnt vmcnt(18)
	ds_write2_b32 v74, v88, v89 offset0:24 offset1:90
	s_waitcnt vmcnt(16)
	ds_write2_b32 v74, v90, v91 offset0:156 offset1:222
	s_waitcnt vmcnt(14)
	ds_write2_b32 v75, v92, v93 offset0:32 offset1:98
	s_waitcnt vmcnt(12)
	ds_write2_b32 v75, v94, v95 offset0:164 offset1:230
	s_waitcnt vmcnt(10)
	ds_write2_b32 v76, v96, v97 offset0:40 offset1:106
	s_waitcnt vmcnt(8)
	ds_write2_b32 v76, v98, v44 offset0:172 offset1:238
	s_waitcnt vmcnt(6)
	ds_write2_b32 v77, v45, v32 offset0:48 offset1:114
	s_waitcnt vmcnt(4)
	ds_write2_b32 v77, v33, v34 offset0:180 offset1:246
	v_add_u32_e32 v4, 0x1c00, v51
	s_waitcnt vmcnt(2)
	ds_write2_b32 v4, v35, v36 offset0:56 offset1:122
	s_waitcnt vmcnt(0)
	ds_write2_b32 v4, v37, v30 offset0:188 offset1:254
	s_waitcnt lgkmcnt(0)
	ds_read2_b32 v[34:35], v53 offset0:33 offset1:41
	ds_read2_b32 v[36:37], v53 offset1:8
	ds_read2_b32 v[38:39], v53 offset0:66 offset1:74
	ds_read2_b32 v[40:41], v53 offset0:99 offset1:107
	ds_read2_b32 v[42:43], v53 offset0:132 offset1:140
	ds_read2_b32 v[44:45], v53 offset0:165 offset1:173
	ds_read2_b32 v[46:47], v53 offset0:198 offset1:206
	ds_read2_b32 v[48:49], v53 offset0:231 offset1:239
	v_or_b32_e32 v4, s0, v52
	v_lshl_add_u64 v[80:81], v[14:15], 0, s[44:45]
	v_lshlrev_b32_e32 v4, 11, v4
	s_waitcnt lgkmcnt(6)
	v_cvt_pk_bf16_f32 v30, v36, v34
	s_waitcnt lgkmcnt(4)
	v_cvt_pk_bf16_f32 v31, v38, v40
	s_waitcnt lgkmcnt(2)
	v_cvt_pk_bf16_f32 v32, v42, v44
	s_waitcnt lgkmcnt(0)
	v_cvt_pk_bf16_f32 v33, v46, v48
	v_lshl_add_u64 v[82:83], v[80:81], 0, v[4:5]
	global_store_dwordx4 v[82:83], v[30:33], off sc1
	v_or_b32_e32 v4, s0, v54
	v_lshlrev_b32_e32 v4, 11, v4
	v_cvt_pk_bf16_f32 v30, v37, v35
	v_cvt_pk_bf16_f32 v31, v39, v41
	v_cvt_pk_bf16_f32 v32, v43, v45
	v_cvt_pk_bf16_f32 v33, v47, v49
	ds_read2_b32 v[36:37], v53 offset0:49 offset1:57
	ds_read2_b32 v[38:39], v53 offset0:16 offset1:24
	ds_read2_b32 v[40:41], v53 offset0:82 offset1:90
	ds_read2_b32 v[42:43], v53 offset0:115 offset1:123
	ds_read2_b32 v[44:45], v53 offset0:148 offset1:156
	ds_read2_b32 v[46:47], v53 offset0:181 offset1:189
	ds_read2_b32 v[48:49], v53 offset0:214 offset1:222
	ds_read2_b32 v[82:83], v53 offset0:247 offset1:255
	v_lshl_add_u64 v[34:35], v[80:81], 0, v[4:5]
	v_or_b32_e32 v4, s0, v55
	v_lshlrev_b32_e32 v4, 11, v4
	global_store_dwordx4 v[34:35], v[30:33], off sc1
	v_lshl_add_u64 v[34:35], v[80:81], 0, v[4:5]
	v_or_b32_e32 v4, s0, v56
	s_waitcnt lgkmcnt(6)
	v_cvt_pk_bf16_f32 v30, v38, v36
	s_waitcnt lgkmcnt(4)
	v_cvt_pk_bf16_f32 v31, v40, v42
	s_waitcnt lgkmcnt(2)
	v_cvt_pk_bf16_f32 v32, v44, v46
	s_waitcnt lgkmcnt(0)
	v_cvt_pk_bf16_f32 v33, v48, v82
	v_lshlrev_b32_e32 v4, 11, v4
	global_store_dwordx4 v[34:35], v[30:33], off sc1
	v_lshl_add_u64 v[34:35], v[80:81], 0, v[4:5]
	s_nop 0
	v_cvt_pk_bf16_f32 v30, v39, v37
	v_cvt_pk_bf16_f32 v31, v41, v43
	v_cvt_pk_bf16_f32 v32, v45, v47
	v_cvt_pk_bf16_f32 v33, v49, v83
	global_store_dwordx4 v[34:35], v[30:33], off sc1
	s_waitcnt lgkmcnt(0)

; template <int MODE> __device__ __forceinline__ void transpose_item(const float* W, int ldw, int K, int N, const float* ks, bf16_t* WT, LAS float* scr, int item, int lane) {
;     ...
;     { float v[32];
; #pragma unroll
;         for (int i = 0; i < 32; ++i) { const int kk = 2 * i + (lane >> 5); v[i] = (sc >= 0) ? W[(size_t)(k0 + kk) * ldw + sc] : 0.f; }
.LBB0_36:
	s_andn2_b64 vcc, exec, s[2:3]
	s_cbranch_vccnz .LBB0_38
	s_and_b32 s1, s65, 0x1c0
	v_or_b32_e32 v4, s1, v2
	s_and_b32 s0, s61, 0x3e0
	v_lshlrev_b32_e32 v4, 10, v4
	v_or3_b32 v4, v4, v1, s0
	v_lshlrev_b32_e32 v4, 2, v4
	v_lshl_add_u64 v[30:31], s[14:15], 0, v[4:5]
	v_add_co_u32_e32 v32, vcc, 0x2000, v30
	global_load_dword v4, v4, s[14:15]
	s_nop 0
	v_addc_co_u32_e32 v33, vcc, 0, v31, vcc
	v_add_co_u32_e32 v34, vcc, 0x4000, v30
	s_lshl_b32 s44, s1, 1
	s_nop 0
	v_addc_co_u32_e32 v35, vcc, 0, v31, vcc
	v_add_co_u32_e32 v36, vcc, 0x6000, v30
	s_nop 1
	v_addc_co_u32_e32 v37, vcc, 0, v31, vcc
	v_add_co_u32_e32 v38, vcc, 0x8000, v30
	s_nop 1
	v_addc_co_u32_e32 v39, vcc, 0, v31, vcc
	v_add_co_u32_e32 v40, vcc, 0xa000, v30
	s_nop 1
	v_addc_co_u32_e32 v41, vcc, 0, v31, vcc
	v_add_co_u32_e32 v42, vcc, 0xc000, v30
	s_nop 1
	v_addc_co_u32_e32 v43, vcc, 0, v31, vcc
	v_add_co_u32_e32 v44, vcc, 0xe000, v30
	s_nop 1
	v_addc_co_u32_e32 v45, vcc, 0, v31, vcc
	v_add_co_u32_e32 v46, vcc, 0x10000, v30
	s_nop 1
	v_addc_co_u32_e32 v47, vcc, 0, v31, vcc
	global_load_dword v48, v[32:33], off
	global_load_dword v49, v[34:35], off
	global_load_dword v79, v[36:37], off
	global_load_dword v80, v[38:39], off
	global_load_dword v81, v[40:41], off
	global_load_dword v82, v[42:43], off
	global_load_dword v83, v[44:45], off
	global_load_dword v84, v[46:47], off
	v_add_co_u32_e32 v32, vcc, 0x12000, v30
	s_nop 1
	v_addc_co_u32_e32 v33, vcc, 0, v31, vcc
	v_add_co_u32_e32 v34, vcc, 0x14000, v30
	s_nop 1
	v_addc_co_u32_e32 v35, vcc, 0, v31, vcc
	v_add_co_u32_e32 v36, vcc, 0x16000, v30
	s_nop 1
	v_addc_co_u32_e32 v37, vcc, 0, v31, vcc
	v_add_co_u32_e32 v38, vcc, 0x18000, v30
	s_nop 1
	v_addc_co_u32_e32 v39, vcc, 0, v31, vcc
	v_add_co_u32_e32 v40, vcc, 0x1a000, v30
	s_nop 1
	v_addc_co_u32_e32 v41, vcc, 0, v31, vcc
	v_add_co_u32_e32 v42, vcc, 0x1c000, v30
	s_nop 1
	v_addc_co_u32_e32 v43, vcc, 0, v31, vcc
	v_add_co_u32_e32 v44, vcc, 0x1e000, v30
	s_nop 1
	v_addc_co_u32_e32 v45, vcc, 0, v31, vcc
	v_add_co_u32_e32 v46, vcc, 0x20000, v30
	s_nop 1
	v_addc_co_u32_e32 v47, vcc, 0, v31, vcc
	global_load_dword v85, v[32:33], off
	global_load_dword v86, v[34:35], off
	global_load_dword v87, v[36:37], off
	global_load_dword v88, v[38:39], off
	global_load_dword v89, v[40:41], off
	global_load_dword v90, v[42:43], off
	global_load_dword v91, v[44:45], off
	global_load_dword v92, v[46:47], off
	v_add_co_u32_e32 v32, vcc, 0x22000, v30
	s_nop 1
	v_addc_co_u32_e32 v33, vcc, 0, v31, vcc
	v_add_co_u32_e32 v34, vcc, 0x24000, v30
	s_nop 1
	v_addc_co_u32_e32 v35, vcc, 0, v31, vcc
	v_add_co_u32_e32 v36, vcc, 0x26000, v30
	s_nop 1
	v_addc_co_u32_e32 v37, vcc, 0, v31, vcc
	v_add_co_u32_e32 v38, vcc, 0x28000, v30
	s_nop 1
	v_addc_co_u32_e32 v39, vcc, 0, v31, vcc
	v_add_co_u32_e32 v40, vcc, 0x2a000, v30
	s_nop 1
	v_addc_co_u32_e32 v41, vcc, 0, v31, vcc
	v_add_co_u32_e32 v42, vcc, 0x2c000, v30
	s_nop 1
	v_addc_co_u32_e32 v43, vcc, 0, v31, vcc
	v_add_co_u32_e32 v44, vcc, 0x2e000, v30
	s_nop 1
	v_addc_co_u32_e32 v45, vcc, 0, v31, vcc
	v_add_co_u32_e32 v46, vcc, 0x30000, v30
	s_nop 1
	v_addc_co_u32_e32 v47, vcc, 0, v31, vcc
	global_load_dword v93, v[32:33], off
	global_load_dword v94, v[34:35], off
	global_load_dword v95, v[36:37], off
	global_load_dword v96, v[38:39], off
	global_load_dword v97, v[40:41], off
	global_load_dword v98, v[42:43], off
	s_nop 0
	global_load_dword v44, v[44:45], off
	s_nop 0
	global_load_dword v45, v[46:47], off
	v_add_co_u32_e32 v32, vcc, 0x32000, v30
	s_nop 1
	v_addc_co_u32_e32 v33, vcc, 0, v31, vcc
	v_add_co_u32_e32 v34, vcc, 0x34000, v30
	s_nop 1
	v_addc_co_u32_e32 v35, vcc, 0, v31, vcc
	v_add_co_u32_e32 v36, vcc, 0x36000, v30
	s_nop 1
	v_addc_co_u32_e32 v37, vcc, 0, v31, vcc
	v_add_co_u32_e32 v38, vcc, 0x38000, v30
	s_nop 1
	v_addc_co_u32_e32 v39, vcc, 0, v31, vcc
	v_add_co_u32_e32 v40, vcc, 0x3a000, v30
	s_nop 1
	v_addc_co_u32_e32 v41, vcc, 0, v31, vcc
	v_add_co_u32_e32 v42, vcc, 0x3c000, v30
	s_nop 1
	v_addc_co_u32_e32 v43, vcc, 0, v31, vcc
	v_add_co_u32_e32 v30, vcc, 0x3e000, v30
	s_nop 1
	v_addc_co_u32_e32 v31, vcc, 0, v31, vcc
	global_load_dword v32, v[32:33], off
	s_nop 0
	global_load_dword v33, v[34:35], off
	s_nop 0
	global_load_dword v34, v[36:37], off
	global_load_dword v35, v[38:39], off
	s_nop 0
	global_load_dword v36, v[40:41], off
	global_load_dword v37, v[42:43], off
	s_nop 0
	global_load_dword v30, v[30:31], off
	s_waitcnt vmcnt(30)
; __device__ __forceinline__ unsigned cvt_pk_bf16(float lo, float hi) { f32x2 v = {lo, hi}; bf16x2_t b = __builtin_convertvector(v, bf16x2_t); return __builtin_bit_cast(unsigned, b); }
; #define LAS __attribute__((address_space(3)))
; #define LDS_WAIT() asm volatile("s_waitcnt lgkmcnt(0)" ::: "memory")
; template <int MODE> __device__ __forceinline__ void transpose_item(const float* W, int ldw, int K, int N, const float* ks, bf16_t* WT, LAS float* scr, int item, int lane) {
;     ...
; #pragma unroll
;         for (int i = 0; i < 32; ++i) { const int kk = 2 * i + (lane >> 5); float x = v[i]; if (ks) x *= ks[k0 + kk]; scr[kk * 33 + (lane & 31)] = x; } }
;     LDS_WAIT(); asm volatile("" ::: "memory");
;     const int c = lane & 7;
; #pragma unroll
;     for (int j = 0; j < 4; ++j) { const int n = (lane >> 3) + 8 * j; const LAS float* s = scr + (8 * c) * 33 + n;
;         u32x4 o; o.x = cvt_pk_bf16(s[0 * 33], s[1 * 33]); o.y = cvt_pk_bf16(s[2 * 33], s[3 * 33]); o.z = cvt_pk_bf16(s[4 * 33], s[5 * 33]); o.w = cvt_pk_bf16(s[6 * 33], s[7 * 33]);
;         *(u32x4*)(WT + (size_t)(n0 + n) * K + k0 + 8 * c) = o; }
;     LDS_WAIT(); asm volatile("" ::: "memory");
	ds_write2_b32 v51, v4, v48 offset1:66
	s_waitcnt vmcnt(28)
	ds_write2_b32 v51, v49, v79 offset0:132 offset1:198
	s_waitcnt vmcnt(26)
	ds_write2_b32 v72, v80, v81 offset0:8 offset1:74
	s_waitcnt vmcnt(24)
	ds_write2_b32 v72, v82, v83 offset0:140 offset1:206
	s_waitcnt vmcnt(22)
	ds_write2_b32 v73, v84, v85 offset0:16 offset1:82
	s_waitcnt vmcnt(20)
	ds_write2_b32 v73, v86, v87 offset0:148 offset1:214
	s_waitcnt vmcnt(18)
	ds_write2_b32 v74, v88, v89 offset0:24 offset1:90
	s_waitcnt vmcnt(16)
	ds_write2_b32 v74, v90, v91 offset0:156 offset1:222
	s_waitcnt vmcnt(14)
	ds_write2_b32 v75, v92, v93 offset0:32 offset1:98
	s_waitcnt vmcnt(12)
	ds_write2_b32 v75, v94, v95 offset0:164 offset1:230
	s_waitcnt vmcnt(10)
	ds_write2_b32 v76, v96, v97 offset0:40 offset1:106
	s_waitcnt vmcnt(8)
	ds_write2_b32 v76, v98, v44 offset0:172 offset1:238
	s_waitcnt vmcnt(6)
	ds_write2_b32 v77, v45, v32 offset0:48 offset1:114
	s_waitcnt vmcnt(4)
	ds_write2_b32 v77, v33, v34 offset0:180 offset1:246
	v_add_u32_e32 v4, 0x1c00, v51
	s_waitcnt vmcnt(2)
	ds_write2_b32 v4, v35, v36 offset0:56 offset1:122
	s_waitcnt vmcnt(0)
	ds_write2_b32 v4, v37, v30 offset0:188 offset1:254
	s_waitcnt lgkmcnt(0)
	ds_read2_b32 v[34:35], v53 offset0:33 offset1:41
	ds_read2_b32 v[36:37], v53 offset1:8
	ds_read2_b32 v[38:39], v53 offset0:66 offset1:74
	ds_read2_b32 v[40:41], v53 offset0:99 offset1:107
	ds_read2_b32 v[42:43], v53 offset0:132 offset1:140
	ds_read2_b32 v[44:45], v53 offset0:165 offset1:173
	ds_read2_b32 v[46:47], v53 offset0:198 offset1:206
	ds_read2_b32 v[48:49], v53 offset0:231 offset1:239
	v_or_b32_e32 v4, s0, v52
	v_lshl_add_u64 v[80:81], v[16:17], 0, s[44:45]
	v_lshlrev_b32_e32 v4, 11, v4
	s_waitcnt lgkmcnt(6)
	v_cvt_pk_bf16_f32 v30, v36, v34
	s_waitcnt lgkmcnt(4)
	v_cvt_pk_bf16_f32 v31, v38, v40
	s_waitcnt lgkmcnt(2)
	v_cvt_pk_bf16_f32 v32, v42, v44
	s_waitcnt lgkmcnt(0)
	v_cvt_pk_bf16_f32 v33, v46, v48
	v_lshl_add_u64 v[82:83], v[80:81], 0, v[4:5]
	global_store_dwordx4 v[82:83], v[30:33], off sc1
	v_or_b32_e32 v4, s0, v54
	v_lshlrev_b32_e32 v4, 11, v4
	v_cvt_pk_bf16_f32 v30, v37, v35
	v_cvt_pk_bf16_f32 v31, v39, v41
	v_cvt_pk_bf16_f32 v32, v43, v45
	v_cvt_pk_bf16_f32 v33, v47, v49
	ds_read2_b32 v[36:37], v53 offset0:49 offset1:57
	ds_read2_b32 v[38:39], v53 offset0:16 offset1:24
	ds_read2_b32 v[40:41], v53 offset0:82 offset1:90
	ds_read2_b32 v[42:43], v53 offset0:115 offset1:123
	ds_read2_b32 v[44:45], v53 offset0:148 offset1:156
	ds_read2_b32 v[46:47], v53 offset0:181 offset1:189
	ds_read2_b32 v[48:49], v53 offset0:214 offset1:222
	ds_read2_b32 v[82:83], v53 offset0:247 offset1:255
	v_lshl_add_u64 v[34:35], v[80:81], 0, v[4:5]
	v_or_b32_e32 v4, s0, v55
	v_lshlrev_b32_e32 v4, 11, v4
	global_store_dwordx4 v[34:35], v[30:33], off sc1
	v_lshl_add_u64 v[34:35], v[80:81], 0, v[4:5]
	v_or_b32_e32 v4, s0, v56
	s_waitcnt lgkmcnt(6)
	v_cvt_pk_bf16_f32 v30, v38, v36
	s_waitcnt lgkmcnt(4)
	v_cvt_pk_bf16_f32 v31, v40, v42
	s_waitcnt lgkmcnt(2)
	v_cvt_pk_bf16_f32 v32, v44, v46
	s_waitcnt lgkmcnt(0)
	v_cvt_pk_bf16_f32 v33, v48, v82
	v_lshlrev_b32_e32 v4, 11, v4
	global_store_dwordx4 v[34:35], v[30:33], off sc1
	v_lshl_add_u64 v[34:35], v[80:81], 0, v[4:5]
	s_nop 0
	v_cvt_pk_bf16_f32 v30, v39, v37
	v_cvt_pk_bf16_f32 v31, v41, v43
	v_cvt_pk_bf16_f32 v32, v45, v47
	v_cvt_pk_bf16_f32 v33, v49, v83
	global_store_dwordx4 v[34:35], v[30:33], off sc1
	s_waitcnt lgkmcnt(0)

; template <int MODE> __device__ __forceinline__ void transpose_item(const float* W, int ldw, int K, int N, const float* ks, bf16_t* WT, LAS float* scr, int item, int lane) {
;     ...
;     { float v[32];
; #pragma unroll
;         for (int i = 0; i < 32; ++i) { const int kk = 2 * i + (lane >> 5); v[i] = (sc >= 0) ? W[(size_t)(k0 + kk) * ldw + sc] : 0.f; }
.LBB0_39:
	s_andn2_b64 vcc, exec, s[2:3]
	s_cbranch_vccnz .LBB0_41
	s_and_b32 s1, s65, 0x1c0
	v_or_b32_e32 v4, s1, v2
	s_and_b32 s0, s61, 0x3e0
	v_lshlrev_b32_e32 v4, 10, v4
	v_or3_b32 v4, v4, v1, s0
	v_lshlrev_b32_e32 v4, 2, v4
	v_lshl_add_u64 v[30:31], s[12:13], 0, v[4:5]
	v_add_co_u32_e32 v32, vcc, 0x2000, v30
	global_load_dword v4, v4, s[12:13]
	s_nop 0
	v_addc_co_u32_e32 v33, vcc, 0, v31, vcc
	v_add_co_u32_e32 v34, vcc, 0x4000, v30
	s_lshl_b32 s44, s1, 1
	s_nop 0
	v_addc_co_u32_e32 v35, vcc, 0, v31, vcc
	v_add_co_u32_e32 v36, vcc, 0x6000, v30
	s_nop 1
	v_addc_co_u32_e32 v37, vcc, 0, v31, vcc
	v_add_co_u32_e32 v38, vcc, 0x8000, v30
	s_nop 1
	v_addc_co_u32_e32 v39, vcc, 0, v31, vcc
	v_add_co_u32_e32 v40, vcc, 0xa000, v30
	s_nop 1
	v_addc_co_u32_e32 v41, vcc, 0, v31, vcc
	v_add_co_u32_e32 v42, vcc, 0xc000, v30
	s_nop 1
	v_addc_co_u32_e32 v43, vcc, 0, v31, vcc
	v_add_co_u32_e32 v44, vcc, 0xe000, v30
	s_nop 1
	v_addc_co_u32_e32 v45, vcc, 0, v31, vcc
	v_add_co_u32_e32 v46, vcc, 0x10000, v30
	s_nop 1
	v_addc_co_u32_e32 v47, vcc, 0, v31, vcc
	global_load_dword v48, v[32:33], off
	global_load_dword v49, v[34:35], off
	global_load_dword v79, v[36:37], off
	global_load_dword v80, v[38:39], off
	global_load_dword v81, v[40:41], off
	global_load_dword v82, v[42:43], off
	global_load_dword v83, v[44:45], off
	global_load_dword v84, v[46:47], off
	v_add_co_u32_e32 v32, vcc, 0x12000, v30
	s_nop 1
	v_addc_co_u32_e32 v33, vcc, 0, v31, vcc
	v_add_co_u32_e32 v34, vcc, 0x14000, v30
	s_nop 1
	v_addc_co_u32_e32 v35, vcc, 0, v31, vcc
	v_add_co_u32_e32 v36, vcc, 0x16000, v30
	s_nop 1
	v_addc_co_u32_e32 v37, vcc, 0, v31, vcc
	v_add_co_u32_e32 v38, vcc, 0x18000, v30
	s_nop 1
	v_addc_co_u32_e32 v39, vcc, 0, v31, vcc
	v_add_co_u32_e32 v40, vcc, 0x1a000, v30
	s_nop 1
	v_addc_co_u32_e32 v41, vcc, 0, v31, vcc
	v_add_co_u32_e32 v42, vcc, 0x1c000, v30
	s_nop 1
	v_addc_co_u32_e32 v43, vcc, 0, v31, vcc
	v_add_co_u32_e32 v44, vcc, 0x1e000, v30
	s_nop 1
	v_addc_co_u32_e32 v45, vcc, 0, v31, vcc
	v_add_co_u32_e32 v46, vcc, 0x20000, v30
	s_nop 1
	v_addc_co_u32_e32 v47, vcc, 0, v31, vcc
	global_load_dword v85, v[32:33], off
	global_load_dword v86, v[34:35], off
	global_load_dword v87, v[36:37], off
	global_load_dword v88, v[38:39], off
	global_load_dword v89, v[40:41], off
	global_load_dword v90, v[42:43], off
	global_load_dword v91, v[44:45], off
	global_load_dword v92, v[46:47], off
	v_add_co_u32_e32 v32, vcc, 0x22000, v30
	s_nop 1
	v_addc_co_u32_e32 v33, vcc, 0, v31, vcc
	v_add_co_u32_e32 v34, vcc, 0x24000, v30
	s_nop 1
	v_addc_co_u32_e32 v35, vcc, 0, v31, vcc
	v_add_co_u32_e32 v36, vcc, 0x26000, v30
	s_nop 1
	v_addc_co_u32_e32 v37, vcc, 0, v31, vcc
	v_add_co_u32_e32 v38, vcc, 0x28000, v30
	s_nop 1
	v_addc_co_u32_e32 v39, vcc, 0, v31, vcc
	v_add_co_u32_e32 v40, vcc, 0x2a000, v30
	s_nop 1
	v_addc_co_u32_e32 v41, vcc, 0, v31, vcc
	v_add_co_u32_e32 v42, vcc, 0x2c000, v30
	s_nop 1
	v_addc_co_u32_e32 v43, vcc, 0, v31, vcc
	v_add_co_u32_e32 v44, vcc, 0x2e000, v30
	s_nop 1
	v_addc_co_u32_e32 v45, vcc, 0, v31, vcc
	v_add_co_u32_e32 v46, vcc, 0x30000, v30
	s_nop 1
	v_addc_co_u32_e32 v47, vcc, 0, v31, vcc
	global_load_dword v93, v[32:33], off
	global_load_dword v94, v[34:35], off
	global_load_dword v95, v[36:37], off
	global_load_dword v96, v[38:39], off
	global_load_dword v97, v[40:41], off
	global_load_dword v98, v[42:43], off
	s_nop 0
	global_load_dword v44, v[44:45], off
	s_nop 0
	global_load_dword v45, v[46:47], off
	v_add_co_u32_e32 v32, vcc, 0x32000, v30
	s_nop 1
	v_addc_co_u32_e32 v33, vcc, 0, v31, vcc
	v_add_co_u32_e32 v34, vcc, 0x34000, v30
	s_nop 1
	v_addc_co_u32_e32 v35, vcc, 0, v31, vcc
	v_add_co_u32_e32 v36, vcc, 0x36000, v30
	s_nop 1
	v_addc_co_u32_e32 v37, vcc, 0, v31, vcc
	v_add_co_u32_e32 v38, vcc, 0x38000, v30
	s_nop 1
	v_addc_co_u32_e32 v39, vcc, 0, v31, vcc
	v_add_co_u32_e32 v40, vcc, 0x3a000, v30
	s_nop 1
	v_addc_co_u32_e32 v41, vcc, 0, v31, vcc
	v_add_co_u32_e32 v42, vcc, 0x3c000, v30
	s_nop 1
	v_addc_co_u32_e32 v43, vcc, 0, v31, vcc
	v_add_co_u32_e32 v30, vcc, 0x3e000, v30
	s_nop 1
	v_addc_co_u32_e32 v31, vcc, 0, v31, vcc
	global_load_dword v32, v[32:33], off
	s_nop 0
	global_load_dword v33, v[34:35], off
	s_nop 0
	global_load_dword v34, v[36:37], off
	global_load_dword v35, v[38:39], off
	s_nop 0
	global_load_dword v36, v[40:41], off
	global_load_dword v37, v[42:43], off
	s_nop 0
	global_load_dword v30, v[30:31], off
	s_waitcnt vmcnt(30)
; __device__ __forceinline__ unsigned cvt_pk_bf16(float lo, float hi) { f32x2 v = {lo, hi}; bf16x2_t b = __builtin_convertvector(v, bf16x2_t); return __builtin_bit_cast(unsigned, b); }
; #define LAS __attribute__((address_space(3)))
; #define LDS_WAIT() asm volatile("s_waitcnt lgkmcnt(0)" ::: "memory")
; template <int MODE> __device__ __forceinline__ void transpose_item(const float* W, int ldw, int K, int N, const float* ks, bf16_t* WT, LAS float* scr, int item, int lane) {
;     ...
; #pragma unroll
;         for (int i = 0; i < 32; ++i) { const int kk = 2 * i + (lane >> 5); float x = v[i]; if (ks) x *= ks[k0 + kk]; scr[kk * 33 + (lane & 31)] = x; } }
;     LDS_WAIT(); asm volatile("" ::: "memory");
;     const int c = lane & 7;
; #pragma unroll
;     for (int j = 0; j < 4; ++j) { const int n = (lane >> 3) + 8 * j; const LAS float* s = scr + (8 * c) * 33 + n;
;         u32x4 o; o.x = cvt_pk_bf16(s[0 * 33], s[1 * 33]); o.y = cvt_pk_bf16(s[2 * 33], s[3 * 33]); o.z = cvt_pk_bf16(s[4 * 33], s[5 * 33]); o.w = cvt_pk_bf16(s[6 * 33], s[7 * 33]);
;         *(u32x4*)(WT + (size_t)(n0 + n) * K + k0 + 8 * c) = o; }
;     LDS_WAIT(); asm volatile("" ::: "memory");
	ds_write2_b32 v51, v4, v48 offset1:66
	s_waitcnt vmcnt(28)
	ds_write2_b32 v51, v49, v79 offset0:132 offset1:198
	s_waitcnt vmcnt(26)
	ds_write2_b32 v72, v80, v81 offset0:8 offset1:74
	s_waitcnt vmcnt(24)
	ds_write2_b32 v72, v82, v83 offset0:140 offset1:206
	s_waitcnt vmcnt(22)
	ds_write2_b32 v73, v84, v85 offset0:16 offset1:82
	s_waitcnt vmcnt(20)
	ds_write2_b32 v73, v86, v87 offset0:148 offset1:214
	s_waitcnt vmcnt(18)
	ds_write2_b32 v74, v88, v89 offset0:24 offset1:90
	s_waitcnt vmcnt(16)
	ds_write2_b32 v74, v90, v91 offset0:156 offset1:222
	s_waitcnt vmcnt(14)
	ds_write2_b32 v75, v92, v93 offset0:32 offset1:98
	s_waitcnt vmcnt(12)
	ds_write2_b32 v75, v94, v95 offset0:164 offset1:230
	s_waitcnt vmcnt(10)
	ds_write2_b32 v76, v96, v97 offset0:40 offset1:106
	s_waitcnt vmcnt(8)
	ds_write2_b32 v76, v98, v44 offset0:172 offset1:238
	s_waitcnt vmcnt(6)
	ds_write2_b32 v77, v45, v32 offset0:48 offset1:114
	s_waitcnt vmcnt(4)
	ds_write2_b32 v77, v33, v34 offset0:180 offset1:246
	v_add_u32_e32 v4, 0x1c00, v51
	s_waitcnt vmcnt(2)
	ds_write2_b32 v4, v35, v36 offset0:56 offset1:122
	s_waitcnt vmcnt(0)
	ds_write2_b32 v4, v37, v30 offset0:188 offset1:254
	s_waitcnt lgkmcnt(0)
	ds_read2_b32 v[34:35], v53 offset0:33 offset1:41
	ds_read2_b32 v[36:37], v53 offset1:8
	ds_read2_b32 v[38:39], v53 offset0:66 offset1:74
	ds_read2_b32 v[40:41], v53 offset0:99 offset1:107
	ds_read2_b32 v[42:43], v53 offset0:132 offset1:140
	ds_read2_b32 v[44:45], v53 offset0:165 offset1:173
	ds_read2_b32 v[46:47], v53 offset0:198 offset1:206
	ds_read2_b32 v[48:49], v53 offset0:231 offset1:239
	v_or_b32_e32 v4, s0, v52
	v_lshl_add_u64 v[80:81], v[18:19], 0, s[44:45]
	v_lshlrev_b32_e32 v4, 11, v4
	s_waitcnt lgkmcnt(6)
	v_cvt_pk_bf16_f32 v30, v36, v34
	s_waitcnt lgkmcnt(4)
	v_cvt_pk_bf16_f32 v31, v38, v40
	s_waitcnt lgkmcnt(2)
	v_cvt_pk_bf16_f32 v32, v42, v44
	s_waitcnt lgkmcnt(0)
	v_cvt_pk_bf16_f32 v33, v46, v48
	v_lshl_add_u64 v[82:83], v[80:81], 0, v[4:5]
	global_store_dwordx4 v[82:83], v[30:33], off sc1
	v_or_b32_e32 v4, s0, v54
	v_lshlrev_b32_e32 v4, 11, v4
	v_cvt_pk_bf16_f32 v30, v37, v35
	v_cvt_pk_bf16_f32 v31, v39, v41
	v_cvt_pk_bf16_f32 v32, v43, v45
	v_cvt_pk_bf16_f32 v33, v47, v49
	ds_read2_b32 v[36:37], v53 offset0:49 offset1:57
	ds_read2_b32 v[38:39], v53 offset0:16 offset1:24
	ds_read2_b32 v[40:41], v53 offset0:82 offset1:90
	ds_read2_b32 v[42:43], v53 offset0:115 offset1:123
	ds_read2_b32 v[44:45], v53 offset0:148 offset1:156
	ds_read2_b32 v[46:47], v53 offset0:181 offset1:189
	ds_read2_b32 v[48:49], v53 offset0:214 offset1:222
	ds_read2_b32 v[82:83], v53 offset0:247 offset1:255
	v_lshl_add_u64 v[34:35], v[80:81], 0, v[4:5]
	v_or_b32_e32 v4, s0, v55
	v_lshlrev_b32_e32 v4, 11, v4
	global_store_dwordx4 v[34:35], v[30:33], off sc1
	v_lshl_add_u64 v[34:35], v[80:81], 0, v[4:5]
	v_or_b32_e32 v4, s0, v56
	s_waitcnt lgkmcnt(6)
	v_cvt_pk_bf16_f32 v30, v38, v36
	s_waitcnt lgkmcnt(4)
	v_cvt_pk_bf16_f32 v31, v40, v42
	s_waitcnt lgkmcnt(2)
	v_cvt_pk_bf16_f32 v32, v44, v46
	s_waitcnt lgkmcnt(0)
	v_cvt_pk_bf16_f32 v33, v48, v82
	v_lshlrev_b32_e32 v4, 11, v4
	global_store_dwordx4 v[34:35], v[30:33], off sc1
	v_lshl_add_u64 v[34:35], v[80:81], 0, v[4:5]
	s_nop 0
	v_cvt_pk_bf16_f32 v30, v39, v37
	v_cvt_pk_bf16_f32 v31, v41, v43
	v_cvt_pk_bf16_f32 v32, v45, v47
	v_cvt_pk_bf16_f32 v33, v49, v83
	global_store_dwordx4 v[34:35], v[30:33], off sc1
	s_waitcnt lgkmcnt(0)

; __device__ __forceinline__ unsigned cvt_pk_bf16(float lo, float hi) { f32x2 v = {lo, hi}; bf16x2_t b = __builtin_convertvector(v, bf16x2_t); return __builtin_bit_cast(unsigned, b); }
; #define LAS __attribute__((address_space(3)))
; #define LDS_WAIT() asm volatile("s_waitcnt lgkmcnt(0)" ::: "memory")
; template <int MODE> __device__ __forceinline__ void transpose_item(const float* W, int ldw, int K, int N, const float* ks, bf16_t* WT, LAS float* scr, int item, int lane) {
;     ...
;     LDS_WAIT(); asm volatile("" ::: "memory");
;     const int c = lane & 7;
; #pragma unroll
;     for (int j = 0; j < 4; ++j) { const int n = (lane >> 3) + 8 * j; const LAS float* s = scr + (8 * c) * 33 + n;
;         u32x4 o; o.x = cvt_pk_bf16(s[0 * 33], s[1 * 33]); o.y = cvt_pk_bf16(s[2 * 33], s[3 * 33]); o.z = cvt_pk_bf16(s[4 * 33], s[5 * 33]); o.w = cvt_pk_bf16(s[6 * 33], s[7 * 33]);
;         *(u32x4*)(WT + (size_t)(n0 + n) * K + k0 + 8 * c) = o; }
;     LDS_WAIT(); asm volatile("" ::: "memory");
.LBB0_145:
	ds_write2_b32 v32, v30, v31 offset0:140 offset1:206
	s_waitcnt lgkmcnt(0)
	ds_read2_b32 v[34:35], v53 offset0:33 offset1:41
	ds_read2_b32 v[36:37], v53 offset1:8
	ds_read2_b32 v[38:39], v53 offset0:66 offset1:74
	ds_read2_b32 v[40:41], v53 offset0:99 offset1:107
	ds_read2_b32 v[42:43], v53 offset0:132 offset1:140
	ds_read2_b32 v[44:45], v53 offset0:165 offset1:173
	ds_read2_b32 v[46:47], v53 offset0:198 offset1:206
	ds_read2_b32 v[48:49], v53 offset0:231 offset1:239
	s_lshl_b32 s44, s1, 1
	v_or_b32_e32 v4, s0, v52
	v_lshl_add_u64 v[80:81], v[20:21], 0, s[44:45]
	v_lshlrev_b32_e32 v4, 11, v4
	s_waitcnt lgkmcnt(6)
	v_cvt_pk_bf16_f32 v30, v36, v34
	s_waitcnt lgkmcnt(4)
	v_cvt_pk_bf16_f32 v31, v38, v40
	s_waitcnt lgkmcnt(2)
	v_cvt_pk_bf16_f32 v32, v42, v44
	s_waitcnt lgkmcnt(0)
	v_cvt_pk_bf16_f32 v33, v46, v48
	v_lshl_add_u64 v[82:83], v[80:81], 0, v[4:5]
	global_store_dwordx4 v[82:83], v[30:33], off sc1
	v_or_b32_e32 v4, s0, v54
	v_lshlrev_b32_e32 v4, 11, v4
	v_cvt_pk_bf16_f32 v30, v37, v35
	v_cvt_pk_bf16_f32 v31, v39, v41
	v_cvt_pk_bf16_f32 v32, v43, v45
	v_cvt_pk_bf16_f32 v33, v47, v49
	ds_read2_b32 v[36:37], v53 offset0:49 offset1:57
	ds_read2_b32 v[38:39], v53 offset0:16 offset1:24
	ds_read2_b32 v[40:41], v53 offset0:82 offset1:90
	ds_read2_b32 v[42:43], v53 offset0:115 offset1:123
	ds_read2_b32 v[44:45], v53 offset0:148 offset1:156
	ds_read2_b32 v[46:47], v53 offset0:181 offset1:189
	ds_read2_b32 v[48:49], v53 offset0:214 offset1:222
	ds_read2_b32 v[82:83], v53 offset0:247 offset1:255
	v_lshl_add_u64 v[34:35], v[80:81], 0, v[4:5]
	v_or_b32_e32 v4, s0, v55
	v_lshlrev_b32_e32 v4, 11, v4
	global_store_dwordx4 v[34:35], v[30:33], off sc1
	v_lshl_add_u64 v[34:35], v[80:81], 0, v[4:5]
	v_or_b32_e32 v4, s0, v56
	s_waitcnt lgkmcnt(6)
	v_cvt_pk_bf16_f32 v30, v38, v36
	s_waitcnt lgkmcnt(4)
	v_cvt_pk_bf16_f32 v31, v40, v42
	s_waitcnt lgkmcnt(2)
	v_cvt_pk_bf16_f32 v32, v44, v46
	s_waitcnt lgkmcnt(0)
	v_cvt_pk_bf16_f32 v33, v48, v82
	v_lshlrev_b32_e32 v4, 11, v4
	global_store_dwordx4 v[34:35], v[30:33], off sc1
	v_lshl_add_u64 v[34:35], v[80:81], 0, v[4:5]
	s_nop 0
	v_cvt_pk_bf16_f32 v30, v39, v37
	v_cvt_pk_bf16_f32 v31, v41, v43
	v_cvt_pk_bf16_f32 v32, v45, v47
	v_cvt_pk_bf16_f32 v33, v49, v83
	global_store_dwordx4 v[34:35], v[30:33], off sc1
	s_waitcnt lgkmcnt(0)

; template <int MODE> __device__ __forceinline__ void transpose_item(const float* W, int ldw, int K, int N, const float* ks, bf16_t* WT, LAS float* scr, int item, int lane) {
;     ...
;     { float v[32];
; #pragma unroll
;         for (int i = 0; i < 32; ++i) { const int kk = 2 * i + (lane >> 5); v[i] = (sc >= 0) ? W[(size_t)(k0 + kk) * ldw + sc] : 0.f; }
.LBB0_147:
	s_andn2_b64 vcc, exec, s[2:3]
	s_cbranch_vccnz .LBB0_149
	s_add_i32 s0, s65, 0x1c900
	s_and_b32 s1, s0, 0x1ffc0
	v_or_b32_e32 v4, s1, v2
	s_and_b32 s0, s61, 0x3e0
	v_lshlrev_b32_e32 v4, 10, v4
	v_or3_b32 v4, v4, v1, s0
	v_lshlrev_b32_e32 v4, 2, v4
	v_lshl_add_u64 v[30:31], s[30:31], 0, v[4:5]
	v_add_co_u32_e32 v32, vcc, 0x2000, v30
	global_load_dword v4, v4, s[30:31]
	s_nop 0
	v_addc_co_u32_e32 v33, vcc, 0, v31, vcc
	v_add_co_u32_e32 v34, vcc, 0x4000, v30
	s_lshl_b32 s44, s1, 1
	s_nop 0
	v_addc_co_u32_e32 v35, vcc, 0, v31, vcc
	v_add_co_u32_e32 v36, vcc, 0x6000, v30
	s_nop 1
	v_addc_co_u32_e32 v37, vcc, 0, v31, vcc
	v_add_co_u32_e32 v38, vcc, 0x8000, v30
	s_nop 1
	v_addc_co_u32_e32 v39, vcc, 0, v31, vcc
	v_add_co_u32_e32 v40, vcc, 0xa000, v30
	s_nop 1
	v_addc_co_u32_e32 v41, vcc, 0, v31, vcc
	v_add_co_u32_e32 v42, vcc, 0xc000, v30
	s_nop 1
	v_addc_co_u32_e32 v43, vcc, 0, v31, vcc
	v_add_co_u32_e32 v44, vcc, 0xe000, v30
	s_nop 1
	v_addc_co_u32_e32 v45, vcc, 0, v31, vcc
	v_add_co_u32_e32 v46, vcc, 0x10000, v30
	s_nop 1
	v_addc_co_u32_e32 v47, vcc, 0, v31, vcc
	global_load_dword v48, v[32:33], off
	global_load_dword v49, v[34:35], off
	global_load_dword v79, v[36:37], off
	global_load_dword v80, v[38:39], off
	global_load_dword v81, v[40:41], off
	global_load_dword v82, v[42:43], off
	global_load_dword v83, v[44:45], off
	global_load_dword v84, v[46:47], off
	v_add_co_u32_e32 v32, vcc, 0x12000, v30
	s_nop 1
	v_addc_co_u32_e32 v33, vcc, 0, v31, vcc
	v_add_co_u32_e32 v34, vcc, 0x14000, v30
	s_nop 1
	v_addc_co_u32_e32 v35, vcc, 0, v31, vcc
	v_add_co_u32_e32 v36, vcc, 0x16000, v30
	s_nop 1
	v_addc_co_u32_e32 v37, vcc, 0, v31, vcc
	v_add_co_u32_e32 v38, vcc, 0x18000, v30
	s_nop 1
	v_addc_co_u32_e32 v39, vcc, 0, v31, vcc
	v_add_co_u32_e32 v40, vcc, 0x1a000, v30
	s_nop 1
	v_addc_co_u32_e32 v41, vcc, 0, v31, vcc
	v_add_co_u32_e32 v42, vcc, 0x1c000, v30
	s_nop 1
	v_addc_co_u32_e32 v43, vcc, 0, v31, vcc
	v_add_co_u32_e32 v44, vcc, 0x1e000, v30
	s_nop 1
	v_addc_co_u32_e32 v45, vcc, 0, v31, vcc
	v_add_co_u32_e32 v46, vcc, 0x20000, v30
	s_nop 1
	v_addc_co_u32_e32 v47, vcc, 0, v31, vcc
	global_load_dword v85, v[32:33], off
	global_load_dword v86, v[34:35], off
	global_load_dword v87, v[36:37], off
	global_load_dword v88, v[38:39], off
	global_load_dword v89, v[40:41], off
	global_load_dword v90, v[42:43], off
	global_load_dword v91, v[44:45], off
	global_load_dword v92, v[46:47], off
	v_add_co_u32_e32 v32, vcc, 0x22000, v30
	s_nop 1
	v_addc_co_u32_e32 v33, vcc, 0, v31, vcc
	v_add_co_u32_e32 v34, vcc, 0x24000, v30
	s_nop 1
	v_addc_co_u32_e32 v35, vcc, 0, v31, vcc
	v_add_co_u32_e32 v36, vcc, 0x26000, v30
	s_nop 1
	v_addc_co_u32_e32 v37, vcc, 0, v31, vcc
	v_add_co_u32_e32 v38, vcc, 0x28000, v30
	s_nop 1
	v_addc_co_u32_e32 v39, vcc, 0, v31, vcc
	v_add_co_u32_e32 v40, vcc, 0x2a000, v30
	s_nop 1
	v_addc_co_u32_e32 v41, vcc, 0, v31, vcc
	v_add_co_u32_e32 v42, vcc, 0x2c000, v30
	s_nop 1
	v_addc_co_u32_e32 v43, vcc, 0, v31, vcc
	v_add_co_u32_e32 v44, vcc, 0x2e000, v30
	s_nop 1
	v_addc_co_u32_e32 v45, vcc, 0, v31, vcc
	v_add_co_u32_e32 v46, vcc, 0x30000, v30
	s_nop 1
	v_addc_co_u32_e32 v47, vcc, 0, v31, vcc
	global_load_dword v93, v[32:33], off
	global_load_dword v94, v[34:35], off
	global_load_dword v95, v[36:37], off
	global_load_dword v96, v[38:39], off
	global_load_dword v97, v[40:41], off
	global_load_dword v98, v[42:43], off
	s_nop 0
	global_load_dword v44, v[44:45], off
	s_nop 0
	global_load_dword v45, v[46:47], off
	v_add_co_u32_e32 v32, vcc, 0x32000, v30
	s_nop 1
	v_addc_co_u32_e32 v33, vcc, 0, v31, vcc
	v_add_co_u32_e32 v34, vcc, 0x34000, v30
	s_nop 1
	v_addc_co_u32_e32 v35, vcc, 0, v31, vcc
	v_add_co_u32_e32 v36, vcc, 0x36000, v30
	s_nop 1
	v_addc_co_u32_e32 v37, vcc, 0, v31, vcc
	v_add_co_u32_e32 v38, vcc, 0x38000, v30
	s_nop 1
	v_addc_co_u32_e32 v39, vcc, 0, v31, vcc
	v_add_co_u32_e32 v40, vcc, 0x3a000, v30
	s_nop 1
	v_addc_co_u32_e32 v41, vcc, 0, v31, vcc
	v_add_co_u32_e32 v42, vcc, 0x3c000, v30
	s_nop 1
	v_addc_co_u32_e32 v43, vcc, 0, v31, vcc
	v_add_co_u32_e32 v30, vcc, 0x3e000, v30
	s_nop 1
	v_addc_co_u32_e32 v31, vcc, 0, v31, vcc
	global_load_dword v32, v[32:33], off
	s_nop 0
	global_load_dword v33, v[34:35], off
	s_nop 0
	global_load_dword v34, v[36:37], off
	global_load_dword v35, v[38:39], off
	s_nop 0
	global_load_dword v36, v[40:41], off
	global_load_dword v37, v[42:43], off
	s_nop 0
	global_load_dword v30, v[30:31], off
	s_waitcnt vmcnt(30)
; __device__ __forceinline__ unsigned cvt_pk_bf16(float lo, float hi) { f32x2 v = {lo, hi}; bf16x2_t b = __builtin_convertvector(v, bf16x2_t); return __builtin_bit_cast(unsigned, b); }
; #define LAS __attribute__((address_space(3)))
; #define LDS_WAIT() asm volatile("s_waitcnt lgkmcnt(0)" ::: "memory")
; template <int MODE> __device__ __forceinline__ void transpose_item(const float* W, int ldw, int K, int N, const float* ks, bf16_t* WT, LAS float* scr, int item, int lane) {
;     ...
; #pragma unroll
;         for (int i = 0; i < 32; ++i) { const int kk = 2 * i + (lane >> 5); float x = v[i]; if (ks) x *= ks[k0 + kk]; scr[kk * 33 + (lane & 31)] = x; } }
;     LDS_WAIT(); asm volatile("" ::: "memory");
;     const int c = lane & 7;
; #pragma unroll
;     for (int j = 0; j < 4; ++j) { const int n = (lane >> 3) + 8 * j; const LAS float* s = scr + (8 * c) * 33 + n;
;         u32x4 o; o.x = cvt_pk_bf16(s[0 * 33], s[1 * 33]); o.y = cvt_pk_bf16(s[2 * 33], s[3 * 33]); o.z = cvt_pk_bf16(s[4 * 33], s[5 * 33]); o.w = cvt_pk_bf16(s[6 * 33], s[7 * 33]);
;         *(u32x4*)(WT + (size_t)(n0 + n) * K + k0 + 8 * c) = o; }
;     LDS_WAIT(); asm volatile("" ::: "memory");
	ds_write2_b32 v51, v4, v48 offset1:66
	s_waitcnt vmcnt(28)
	ds_write2_b32 v51, v49, v79 offset0:132 offset1:198
	s_waitcnt vmcnt(26)
	ds_write2_b32 v72, v80, v81 offset0:8 offset1:74
	s_waitcnt vmcnt(24)
	ds_write2_b32 v72, v82, v83 offset0:140 offset1:206
	s_waitcnt vmcnt(22)
	ds_write2_b32 v73, v84, v85 offset0:16 offset1:82
	s_waitcnt vmcnt(20)
	ds_write2_b32 v73, v86, v87 offset0:148 offset1:214
	s_waitcnt vmcnt(18)
	ds_write2_b32 v74, v88, v89 offset0:24 offset1:90
	s_waitcnt vmcnt(16)
	ds_write2_b32 v74, v90, v91 offset0:156 offset1:222
	s_waitcnt vmcnt(14)
	ds_write2_b32 v75, v92, v93 offset0:32 offset1:98
	s_waitcnt vmcnt(12)
	ds_write2_b32 v75, v94, v95 offset0:164 offset1:230
	s_waitcnt vmcnt(10)
	ds_write2_b32 v76, v96, v97 offset0:40 offset1:106
	s_waitcnt vmcnt(8)
	ds_write2_b32 v76, v98, v44 offset0:172 offset1:238
	s_waitcnt vmcnt(6)
	ds_write2_b32 v77, v45, v32 offset0:48 offset1:114
	s_waitcnt vmcnt(4)
	ds_write2_b32 v77, v33, v34 offset0:180 offset1:246
	v_add_u32_e32 v4, 0x1c00, v51
	s_waitcnt vmcnt(2)
	ds_write2_b32 v4, v35, v36 offset0:56 offset1:122
	s_waitcnt vmcnt(0)
	ds_write2_b32 v4, v37, v30 offset0:188 offset1:254
	s_waitcnt lgkmcnt(0)
	ds_read2_b32 v[34:35], v53 offset0:33 offset1:41
	ds_read2_b32 v[36:37], v53 offset1:8
	ds_read2_b32 v[38:39], v53 offset0:66 offset1:74
	ds_read2_b32 v[40:41], v53 offset0:99 offset1:107
	ds_read2_b32 v[42:43], v53 offset0:132 offset1:140
	ds_read2_b32 v[44:45], v53 offset0:165 offset1:173
	ds_read2_b32 v[46:47], v53 offset0:198 offset1:206
	ds_read2_b32 v[48:49], v53 offset0:231 offset1:239
	v_or_b32_e32 v4, s0, v52
	v_mul_u32_u24_e32 v4, 0xb00, v4
	v_lshl_add_u64 v[80:81], v[22:23], 0, s[44:45]
	v_lshlrev_b32_e32 v4, 1, v4
	v_lshl_add_u64 v[82:83], v[80:81], 0, v[4:5]
	v_or_b32_e32 v4, s0, v54
	s_waitcnt lgkmcnt(6)
	v_cvt_pk_bf16_f32 v30, v36, v34
	s_waitcnt lgkmcnt(4)
	v_cvt_pk_bf16_f32 v31, v38, v40
	s_waitcnt lgkmcnt(2)
	v_cvt_pk_bf16_f32 v32, v42, v44
	s_waitcnt lgkmcnt(0)
	v_cvt_pk_bf16_f32 v33, v46, v48
	v_mul_u32_u24_e32 v4, 0xb00, v4
	global_store_dwordx4 v[82:83], v[30:33], off sc1
	v_lshlrev_b32_e32 v4, 1, v4
	s_nop 0
	v_cvt_pk_bf16_f32 v30, v37, v35
	v_cvt_pk_bf16_f32 v31, v39, v41
	v_cvt_pk_bf16_f32 v32, v43, v45
	v_cvt_pk_bf16_f32 v33, v47, v49
	v_lshl_add_u64 v[34:35], v[80:81], 0, v[4:5]
	ds_read2_b32 v[36:37], v53 offset0:16 offset1:24
	ds_read2_b32 v[38:39], v53 offset0:49 offset1:57
	ds_read2_b32 v[40:41], v53 offset0:82 offset1:90
	ds_read2_b32 v[42:43], v53 offset0:115 offset1:123
	ds_read2_b32 v[44:45], v53 offset0:148 offset1:156
	ds_read2_b32 v[46:47], v53 offset0:181 offset1:189
	ds_read2_b32 v[48:49], v53 offset0:214 offset1:222
	ds_read2_b32 v[82:83], v53 offset0:247 offset1:255
	v_or_b32_e32 v4, s0, v55
	v_mul_u32_u24_e32 v4, 0xb00, v4
	v_lshlrev_b32_e32 v4, 1, v4
	global_store_dwordx4 v[34:35], v[30:33], off sc1
	v_lshl_add_u64 v[34:35], v[80:81], 0, v[4:5]
	v_or_b32_e32 v4, s0, v56
	v_mul_u32_u24_e32 v4, 0xb00, v4
	s_waitcnt lgkmcnt(6)
	v_cvt_pk_bf16_f32 v30, v36, v38
	s_waitcnt lgkmcnt(4)
	v_cvt_pk_bf16_f32 v31, v40, v42
	s_waitcnt lgkmcnt(2)
	v_cvt_pk_bf16_f32 v32, v44, v46
	s_waitcnt lgkmcnt(0)
	v_cvt_pk_bf16_f32 v33, v48, v82
	v_lshlrev_b32_e32 v4, 1, v4
	global_store_dwordx4 v[34:35], v[30:33], off sc1
	v_lshl_add_u64 v[34:35], v[80:81], 0, v[4:5]
	s_nop 0
	v_cvt_pk_bf16_f32 v30, v37, v39
	v_cvt_pk_bf16_f32 v31, v41, v43
	v_cvt_pk_bf16_f32 v32, v45, v47
	v_cvt_pk_bf16_f32 v33, v49, v83
	global_store_dwordx4 v[34:35], v[30:33], off sc1
	s_waitcnt lgkmcnt(0)

; template <int MODE> __device__ __forceinline__ void transpose_item(const float* W, int ldw, int K, int N, const float* ks, bf16_t* WT, LAS float* scr, int item, int lane) {
;     ...
;     { float v[32];
; #pragma unroll
;         for (int i = 0; i < 32; ++i) { const int kk = 2 * i + (lane >> 5); v[i] = (sc >= 0) ? W[(size_t)(k0 + kk) * ldw + sc] : 0.f; }
.LBB0_150:
	s_andn2_b64 vcc, exec, s[2:3]
	s_cbranch_vccnz .LBB0_152
	s_add_i32 s0, s65, 0x1d400
	s_and_b32 s1, s0, 0x1ffc0
	v_or_b32_e32 v4, s1, v2
	s_and_b32 s0, s61, 0x3e0
	v_lshlrev_b32_e32 v4, 10, v4
	v_or3_b32 v4, v4, v1, s0
	v_lshlrev_b32_e32 v4, 2, v4
	v_lshl_add_u64 v[30:31], s[24:25], 0, v[4:5]
	v_add_co_u32_e32 v32, vcc, 0x2000, v30
	global_load_dword v4, v4, s[24:25]
	s_nop 0
	v_addc_co_u32_e32 v33, vcc, 0, v31, vcc
	v_add_co_u32_e32 v34, vcc, 0x4000, v30
	s_lshl_b32 s44, s1, 1
	s_nop 0
	v_addc_co_u32_e32 v35, vcc, 0, v31, vcc
	v_add_co_u32_e32 v36, vcc, 0x6000, v30
	s_nop 1
	v_addc_co_u32_e32 v37, vcc, 0, v31, vcc
	v_add_co_u32_e32 v38, vcc, 0x8000, v30
	s_nop 1
	v_addc_co_u32_e32 v39, vcc, 0, v31, vcc
	v_add_co_u32_e32 v40, vcc, 0xa000, v30
	s_nop 1
	v_addc_co_u32_e32 v41, vcc, 0, v31, vcc
	v_add_co_u32_e32 v42, vcc, 0xc000, v30
	s_nop 1
	v_addc_co_u32_e32 v43, vcc, 0, v31, vcc
	v_add_co_u32_e32 v44, vcc, 0xe000, v30
	s_nop 1
	v_addc_co_u32_e32 v45, vcc, 0, v31, vcc
	v_add_co_u32_e32 v46, vcc, 0x10000, v30
	s_nop 1
	v_addc_co_u32_e32 v47, vcc, 0, v31, vcc
	global_load_dword v48, v[32:33], off
	global_load_dword v49, v[34:35], off
	global_load_dword v79, v[36:37], off
	global_load_dword v80, v[38:39], off
	global_load_dword v81, v[40:41], off
	global_load_dword v82, v[42:43], off
	global_load_dword v83, v[44:45], off
	global_load_dword v84, v[46:47], off
	v_add_co_u32_e32 v32, vcc, 0x12000, v30
	s_nop 1
	v_addc_co_u32_e32 v33, vcc, 0, v31, vcc
	v_add_co_u32_e32 v34, vcc, 0x14000, v30
	s_nop 1
	v_addc_co_u32_e32 v35, vcc, 0, v31, vcc
	v_add_co_u32_e32 v36, vcc, 0x16000, v30
	s_nop 1
	v_addc_co_u32_e32 v37, vcc, 0, v31, vcc
	v_add_co_u32_e32 v38, vcc, 0x18000, v30
	s_nop 1
	v_addc_co_u32_e32 v39, vcc, 0, v31, vcc
	v_add_co_u32_e32 v40, vcc, 0x1a000, v30
	s_nop 1
	v_addc_co_u32_e32 v41, vcc, 0, v31, vcc
	v_add_co_u32_e32 v42, vcc, 0x1c000, v30
	s_nop 1
	v_addc_co_u32_e32 v43, vcc, 0, v31, vcc
	v_add_co_u32_e32 v44, vcc, 0x1e000, v30
	s_nop 1
	v_addc_co_u32_e32 v45, vcc, 0, v31, vcc
	v_add_co_u32_e32 v46, vcc, 0x20000, v30
	s_nop 1
	v_addc_co_u32_e32 v47, vcc, 0, v31, vcc
	global_load_dword v85, v[32:33], off
	global_load_dword v86, v[34:35], off
	global_load_dword v87, v[36:37], off
	global_load_dword v88, v[38:39], off
	global_load_dword v89, v[40:41], off
	global_load_dword v90, v[42:43], off
	global_load_dword v91, v[44:45], off
	global_load_dword v92, v[46:47], off
	v_add_co_u32_e32 v32, vcc, 0x22000, v30
	s_nop 1
	v_addc_co_u32_e32 v33, vcc, 0, v31, vcc
	v_add_co_u32_e32 v34, vcc, 0x24000, v30
	s_nop 1
	v_addc_co_u32_e32 v35, vcc, 0, v31, vcc
	v_add_co_u32_e32 v36, vcc, 0x26000, v30
	s_nop 1
	v_addc_co_u32_e32 v37, vcc, 0, v31, vcc
	v_add_co_u32_e32 v38, vcc, 0x28000, v30
	s_nop 1
	v_addc_co_u32_e32 v39, vcc, 0, v31, vcc
	v_add_co_u32_e32 v40, vcc, 0x2a000, v30
	s_nop 1
	v_addc_co_u32_e32 v41, vcc, 0, v31, vcc
	v_add_co_u32_e32 v42, vcc, 0x2c000, v30
	s_nop 1
	v_addc_co_u32_e32 v43, vcc, 0, v31, vcc
	v_add_co_u32_e32 v44, vcc, 0x2e000, v30
	s_nop 1
	v_addc_co_u32_e32 v45, vcc, 0, v31, vcc
	v_add_co_u32_e32 v46, vcc, 0x30000, v30
	s_nop 1
	v_addc_co_u32_e32 v47, vcc, 0, v31, vcc
	global_load_dword v93, v[32:33], off
	global_load_dword v94, v[34:35], off
	global_load_dword v95, v[36:37], off
	global_load_dword v96, v[38:39], off
	global_load_dword v97, v[40:41], off
	global_load_dword v98, v[42:43], off
	s_nop 0
	global_load_dword v44, v[44:45], off
	s_nop 0
	global_load_dword v45, v[46:47], off
	v_add_co_u32_e32 v32, vcc, 0x32000, v30
	s_nop 1
	v_addc_co_u32_e32 v33, vcc, 0, v31, vcc
	v_add_co_u32_e32 v34, vcc, 0x34000, v30
	s_nop 1
	v_addc_co_u32_e32 v35, vcc, 0, v31, vcc
	v_add_co_u32_e32 v36, vcc, 0x36000, v30
	s_nop 1
	v_addc_co_u32_e32 v37, vcc, 0, v31, vcc
	v_add_co_u32_e32 v38, vcc, 0x38000, v30
	s_nop 1
	v_addc_co_u32_e32 v39, vcc, 0, v31, vcc
	v_add_co_u32_e32 v40, vcc, 0x3a000, v30
	s_nop 1
	v_addc_co_u32_e32 v41, vcc, 0, v31, vcc
	v_add_co_u32_e32 v42, vcc, 0x3c000, v30
	s_nop 1
	v_addc_co_u32_e32 v43, vcc, 0, v31, vcc
	v_add_co_u32_e32 v30, vcc, 0x3e000, v30
	s_nop 1
	v_addc_co_u32_e32 v31, vcc, 0, v31, vcc
	global_load_dword v32, v[32:33], off
	s_nop 0
	global_load_dword v33, v[34:35], off
	s_nop 0
	global_load_dword v34, v[36:37], off
	global_load_dword v35, v[38:39], off
	s_nop 0
	global_load_dword v36, v[40:41], off
	global_load_dword v37, v[42:43], off
	s_nop 0
	global_load_dword v30, v[30:31], off
	s_waitcnt vmcnt(30)
; __device__ __forceinline__ unsigned cvt_pk_bf16(float lo, float hi) { f32x2 v = {lo, hi}; bf16x2_t b = __builtin_convertvector(v, bf16x2_t); return __builtin_bit_cast(unsigned, b); }
; #define LAS __attribute__((address_space(3)))
; #define LDS_WAIT() asm volatile("s_waitcnt lgkmcnt(0)" ::: "memory")
; template <int MODE> __device__ __forceinline__ void transpose_item(const float* W, int ldw, int K, int N, const float* ks, bf16_t* WT, LAS float* scr, int item, int lane) {
;     ...
; #pragma unroll
;         for (int i = 0; i < 32; ++i) { const int kk = 2 * i + (lane >> 5); float x = v[i]; if (ks) x *= ks[k0 + kk]; scr[kk * 33 + (lane & 31)] = x; } }
;     LDS_WAIT(); asm volatile("" ::: "memory");
;     const int c = lane & 7;
; #pragma unroll
;     for (int j = 0; j < 4; ++j) { const int n = (lane >> 3) + 8 * j; const LAS float* s = scr + (8 * c) * 33 + n;
;         u32x4 o; o.x = cvt_pk_bf16(s[0 * 33], s[1 * 33]); o.y = cvt_pk_bf16(s[2 * 33], s[3 * 33]); o.z = cvt_pk_bf16(s[4 * 33], s[5 * 33]); o.w = cvt_pk_bf16(s[6 * 33], s[7 * 33]);
;         *(u32x4*)(WT + (size_t)(n0 + n) * K + k0 + 8 * c) = o; }
;     LDS_WAIT(); asm volatile("" ::: "memory");
	ds_write2_b32 v51, v4, v48 offset1:66
	s_waitcnt vmcnt(28)
	ds_write2_b32 v51, v49, v79 offset0:132 offset1:198
	s_waitcnt vmcnt(26)
	ds_write2_b32 v72, v80, v81 offset0:8 offset1:74
	s_waitcnt vmcnt(24)
	ds_write2_b32 v72, v82, v83 offset0:140 offset1:206
	s_waitcnt vmcnt(22)
	ds_write2_b32 v73, v84, v85 offset0:16 offset1:82
	s_waitcnt vmcnt(20)
	ds_write2_b32 v73, v86, v87 offset0:148 offset1:214
	s_waitcnt vmcnt(18)
	ds_write2_b32 v74, v88, v89 offset0:24 offset1:90
	s_waitcnt vmcnt(16)
	ds_write2_b32 v74, v90, v91 offset0:156 offset1:222
	s_waitcnt vmcnt(14)
	ds_write2_b32 v75, v92, v93 offset0:32 offset1:98
	s_waitcnt vmcnt(12)
	ds_write2_b32 v75, v94, v95 offset0:164 offset1:230
	s_waitcnt vmcnt(10)
	ds_write2_b32 v76, v96, v97 offset0:40 offset1:106
	s_waitcnt vmcnt(8)
	ds_write2_b32 v76, v98, v44 offset0:172 offset1:238
	s_waitcnt vmcnt(6)
	ds_write2_b32 v77, v45, v32 offset0:48 offset1:114
	s_waitcnt vmcnt(4)
	ds_write2_b32 v77, v33, v34 offset0:180 offset1:246
	v_add_u32_e32 v4, 0x1c00, v51
	s_waitcnt vmcnt(2)
	ds_write2_b32 v4, v35, v36 offset0:56 offset1:122
	s_waitcnt vmcnt(0)
	ds_write2_b32 v4, v37, v30 offset0:188 offset1:254
	s_waitcnt lgkmcnt(0)
	ds_read2_b32 v[34:35], v53 offset0:33 offset1:41
	ds_read2_b32 v[36:37], v53 offset1:8
	ds_read2_b32 v[38:39], v53 offset0:66 offset1:74
	ds_read2_b32 v[40:41], v53 offset0:99 offset1:107
	ds_read2_b32 v[42:43], v53 offset0:132 offset1:140
	ds_read2_b32 v[44:45], v53 offset0:165 offset1:173
	ds_read2_b32 v[46:47], v53 offset0:198 offset1:206
	ds_read2_b32 v[48:49], v53 offset0:231 offset1:239
	v_or_b32_e32 v4, s0, v52
	v_mul_u32_u24_e32 v4, 0xb00, v4
	v_lshl_add_u64 v[80:81], v[24:25], 0, s[44:45]
	v_lshlrev_b32_e32 v4, 1, v4
	v_lshl_add_u64 v[82:83], v[80:81], 0, v[4:5]
	v_or_b32_e32 v4, s0, v54
	s_waitcnt lgkmcnt(6)
	v_cvt_pk_bf16_f32 v30, v36, v34
	s_waitcnt lgkmcnt(4)
	v_cvt_pk_bf16_f32 v31, v38, v40
	s_waitcnt lgkmcnt(2)
	v_cvt_pk_bf16_f32 v32, v42, v44
	s_waitcnt lgkmcnt(0)
	v_cvt_pk_bf16_f32 v33, v46, v48
	v_mul_u32_u24_e32 v4, 0xb00, v4
	global_store_dwordx4 v[82:83], v[30:33], off sc1
	v_lshlrev_b32_e32 v4, 1, v4
	s_nop 0
	v_cvt_pk_bf16_f32 v30, v37, v35
	v_cvt_pk_bf16_f32 v31, v39, v41
	v_cvt_pk_bf16_f32 v32, v43, v45
	v_cvt_pk_bf16_f32 v33, v47, v49
	v_lshl_add_u64 v[34:35], v[80:81], 0, v[4:5]
	ds_read2_b32 v[36:37], v53 offset0:16 offset1:24
	ds_read2_b32 v[38:39], v53 offset0:49 offset1:57
	ds_read2_b32 v[40:41], v53 offset0:82 offset1:90
	ds_read2_b32 v[42:43], v53 offset0:115 offset1:123
	ds_read2_b32 v[44:45], v53 offset0:148 offset1:156
	ds_read2_b32 v[46:47], v53 offset0:181 offset1:189
	ds_read2_b32 v[48:49], v53 offset0:214 offset1:222
	ds_read2_b32 v[82:83], v53 offset0:247 offset1:255
	v_or_b32_e32 v4, s0, v55
	v_mul_u32_u24_e32 v4, 0xb00, v4
	v_lshlrev_b32_e32 v4, 1, v4
	global_store_dwordx4 v[34:35], v[30:33], off sc1
	v_lshl_add_u64 v[34:35], v[80:81], 0, v[4:5]
	v_or_b32_e32 v4, s0, v56
	v_mul_u32_u24_e32 v4, 0xb00, v4
	s_waitcnt lgkmcnt(6)
	v_cvt_pk_bf16_f32 v30, v36, v38
	s_waitcnt lgkmcnt(4)
	v_cvt_pk_bf16_f32 v31, v40, v42
	s_waitcnt lgkmcnt(2)
	v_cvt_pk_bf16_f32 v32, v44, v46
	s_waitcnt lgkmcnt(0)
	v_cvt_pk_bf16_f32 v33, v48, v82
	v_lshlrev_b32_e32 v4, 1, v4
	global_store_dwordx4 v[34:35], v[30:33], off sc1
	v_lshl_add_u64 v[34:35], v[80:81], 0, v[4:5]
	s_nop 0
	v_cvt_pk_bf16_f32 v30, v37, v39
	v_cvt_pk_bf16_f32 v31, v41, v43
	v_cvt_pk_bf16_f32 v32, v45, v47
	v_cvt_pk_bf16_f32 v33, v49, v83
	global_store_dwordx4 v[34:35], v[30:33], off sc1
	s_waitcnt lgkmcnt(0)

; __device__ __forceinline__ unsigned cvt_pk_bf16(float lo, float hi) { f32x2 v = {lo, hi}; bf16x2_t b = __builtin_convertvector(v, bf16x2_t); return __builtin_bit_cast(unsigned, b); }
; #define LAS __attribute__((address_space(3)))
; #define LDS_WAIT() asm volatile("s_waitcnt lgkmcnt(0)" ::: "memory")
; template <int MODE> __device__ __forceinline__ void transpose_item(const float* W, int ldw, int K, int N, const float* ks, bf16_t* WT, LAS float* scr, int item, int lane) {
;     ...
;     LDS_WAIT(); asm volatile("" ::: "memory");
;     const int c = lane & 7;
; #pragma unroll
;     for (int j = 0; j < 4; ++j) { const int n = (lane >> 3) + 8 * j; const LAS float* s = scr + (8 * c) * 33 + n;
;         u32x4 o; o.x = cvt_pk_bf16(s[0 * 33], s[1 * 33]); o.y = cvt_pk_bf16(s[2 * 33], s[3 * 33]); o.z = cvt_pk_bf16(s[4 * 33], s[5 * 33]); o.w = cvt_pk_bf16(s[6 * 33], s[7 * 33]);
;         *(u32x4*)(WT + (size_t)(n0 + n) * K + k0 + 8 * c) = o; }
;     LDS_WAIT(); asm volatile("" ::: "memory");
.LBB0_178:
	ds_write2_b32 v34, v32, v33 offset0:140 offset1:206
	s_waitcnt lgkmcnt(0)
	s_waitcnt vmcnt(4)
	ds_read2_b32 v[34:35], v53 offset0:33 offset1:41
	ds_read2_b32 v[36:37], v53 offset1:8
	ds_read2_b32 v[38:39], v53 offset0:66 offset1:74
	ds_read2_b32 v[40:41], v53 offset0:99 offset1:107
	ds_read2_b32 v[42:43], v53 offset0:132 offset1:140
	ds_read2_b32 v[44:45], v53 offset0:165 offset1:173
	ds_read2_b32 v[46:47], v53 offset0:198 offset1:206
	s_waitcnt vmcnt(2)
	ds_read2_b32 v[48:49], v53 offset0:231 offset1:239
	s_lshl_b32 s44, s1, 1
	v_or_b32_e32 v4, s0, v52
	v_lshl_add_u64 v[80:81], v[26:27], 0, s[44:45]
	v_lshlrev_b32_e32 v4, 11, v4
	s_waitcnt vmcnt(1) lgkmcnt(6)
	v_cvt_pk_bf16_f32 v30, v36, v34
	s_waitcnt vmcnt(0) lgkmcnt(4)
	v_cvt_pk_bf16_f32 v31, v38, v40
	s_waitcnt lgkmcnt(2)
	v_cvt_pk_bf16_f32 v32, v42, v44
	s_waitcnt lgkmcnt(0)
	v_cvt_pk_bf16_f32 v33, v46, v48
	v_lshl_add_u64 v[82:83], v[80:81], 0, v[4:5]
	global_store_dwordx4 v[82:83], v[30:33], off sc1
	v_or_b32_e32 v4, s0, v54
	v_lshlrev_b32_e32 v4, 11, v4
	v_cvt_pk_bf16_f32 v30, v37, v35
	v_cvt_pk_bf16_f32 v31, v39, v41
	v_cvt_pk_bf16_f32 v32, v43, v45
	v_cvt_pk_bf16_f32 v33, v47, v49
	ds_read2_b32 v[36:37], v53 offset0:49 offset1:57
	ds_read2_b32 v[38:39], v53 offset0:16 offset1:24
	ds_read2_b32 v[40:41], v53 offset0:82 offset1:90
	ds_read2_b32 v[42:43], v53 offset0:115 offset1:123
	ds_read2_b32 v[44:45], v53 offset0:148 offset1:156
	ds_read2_b32 v[46:47], v53 offset0:181 offset1:189
	ds_read2_b32 v[48:49], v53 offset0:214 offset1:222
	ds_read2_b32 v[82:83], v53 offset0:247 offset1:255
	v_lshl_add_u64 v[34:35], v[80:81], 0, v[4:5]
	v_or_b32_e32 v4, s0, v55
	v_lshlrev_b32_e32 v4, 11, v4
	global_store_dwordx4 v[34:35], v[30:33], off sc1
	v_lshl_add_u64 v[34:35], v[80:81], 0, v[4:5]
	v_or_b32_e32 v4, s0, v56
	s_waitcnt lgkmcnt(6)
	v_cvt_pk_bf16_f32 v30, v38, v36
	s_waitcnt lgkmcnt(4)
	v_cvt_pk_bf16_f32 v31, v40, v42
	s_waitcnt lgkmcnt(2)
	v_cvt_pk_bf16_f32 v32, v44, v46
	s_waitcnt lgkmcnt(0)
	v_cvt_pk_bf16_f32 v33, v48, v82
	v_lshlrev_b32_e32 v4, 11, v4
	global_store_dwordx4 v[34:35], v[30:33], off sc1
	v_lshl_add_u64 v[34:35], v[80:81], 0, v[4:5]
	s_nop 0
	v_cvt_pk_bf16_f32 v30, v39, v37
	v_cvt_pk_bf16_f32 v31, v41, v43
	v_cvt_pk_bf16_f32 v32, v45, v47
	v_cvt_pk_bf16_f32 v33, v49, v83
	global_store_dwordx4 v[34:35], v[30:33], off sc1
	s_waitcnt lgkmcnt(0)

; __device__ __forceinline__ void prep_phase(const Args& a, LAS unsigned char* lds, int vcu, int G, int wave, int lane) {
;     ...
;     for (int m = gw; m < MTOK; m += 4 * NGW) {
;         f32x4 v[4][4]; float s[4];
; #pragma unroll
;         for (int r = 0; r < 4; ++r) { const int mr = m + r * NGW; const f32x4* xr = (const f32x4*)(x + (size_t)(mr < MTOK ? mr : m) * DM) + lane;
; #pragma unroll
;             for (int j = 0; j < 4; ++j) v[r][j] = xr[64 * j]; }
; #pragma unroll
;         for (int r = 0; r < 4; ++r) { float t = 0.f;
; #pragma unroll
;             for (int j = 0; j < 4; ++j) t += (v[r][j][0] * v[r][j][0] + v[r][j][1] * v[r][j][1]) + (v[r][j][2] * v[r][j][2] + v[r][j][3] * v[r][j][3]);
;             s[r] = wave_sum(t); }
.LBB0_296:
	s_ashr_i32 s13, s12, 31
	s_lshl_b64 s[2:3], s[12:13], 12
	v_lshl_add_u64 v[0:1], v[64:65], 0, s[2:3]
	s_add_i32 s2, s12, s59
	s_cmp_lt_i32 s2, 0x8000
	s_cselect_b32 s4, s2, s12
	global_load_dwordx4 v[60:63], v[0:1], off
	global_load_dwordx4 v[56:59], v[0:1], off offset:1024
	global_load_dwordx4 v[40:43], v[0:1], off offset:3072
	global_load_dwordx4 v[52:55], v[0:1], off offset:2048
	s_ashr_i32 s5, s4, 31
	s_lshl_b64 s[4:5], s[4:5], 12
	s_add_i32 s8, s0, s12
	s_cmp_lt_i32 s8, 0x8000
	s_cselect_b64 s[10:11], -1, 0
	v_lshl_add_u64 v[0:1], v[64:65], 0, s[4:5]
	s_and_b64 s[4:5], s[10:11], exec
	global_load_dwordx4 v[48:51], v[0:1], off
	global_load_dwordx4 v[44:47], v[0:1], off offset:1024
	global_load_dwordx4 v[36:39], v[0:1], off offset:2048
	global_load_dwordx4 v[32:35], v[0:1], off offset:3072
	s_cselect_b32 s4, s8, s12
	s_ashr_i32 s5, s4, 31
	s_lshl_b64 s[4:5], s[4:5], 12
	v_lshl_add_u64 v[0:1], v[64:65], 0, s[4:5]
	global_load_dwordx4 v[28:31], v[0:1], off
	global_load_dwordx4 v[24:27], v[0:1], off offset:1024
	global_load_dwordx4 v[20:23], v[0:1], off offset:2048
	global_load_dwordx4 v[16:19], v[0:1], off offset:3072
	s_add_i32 s4, s1, s12
	s_cmp_lt_i32 s4, 0x8000
	s_cselect_b64 s[6:7], -1, 0
	s_and_b64 s[14:15], s[6:7], exec
	s_cselect_b32 s14, s4, s12
	s_ashr_i32 s15, s14, 31
	s_lshl_b64 s[14:15], s[14:15], 12
	s_waitcnt lgkmcnt(0)
	v_lshl_add_u64 v[84:85], v[64:65], 0, s[14:15]
	global_load_dwordx4 v[12:15], v[84:85], off
	global_load_dwordx4 v[8:11], v[84:85], off offset:1024
	global_load_dwordx4 v[4:7], v[84:85], off offset:2048
	global_load_dwordx4 v[0:3], v[84:85], off offset:3072
	s_lshl_b64 s[12:13], s[12:13], 11
	s_cmpk_gt_i32 s2, 0x7fff
	s_waitcnt vmcnt(15)
	v_pk_mul_f32 v[84:85], v[62:63], v[62:63]
	v_pk_mul_f32 v[86:87], v[60:61], v[60:61]
	s_waitcnt vmcnt(14)
	v_pk_mul_f32 v[88:89], v[58:59], v[58:59]
	v_pk_mul_f32 v[90:91], v[56:57], v[56:57]
	v_pk_mov_b32 v[96:97], v[86:87], v[84:85] op_sel:[1,0]
	v_mov_b32_e32 v87, v85
	v_pk_mov_b32 v[84:85], v[90:91], v[88:89] op_sel:[1,0]
	v_mov_b32_e32 v91, v89
	s_waitcnt vmcnt(13)
	v_mul_f32_e32 v95, v40, v40
	s_waitcnt vmcnt(12)
	v_mul_f32_e32 v92, v53, v53
	v_mul_f32_e32 v94, v55, v55
	v_pk_add_f32 v[86:87], v[96:97], v[86:87]
	v_pk_add_f32 v[84:85], v[84:85], v[90:91]
	v_mul_f32_e32 v98, v41, v41
	v_mul_f32_e32 v99, v42, v42
	v_mul_f32_e32 v100, v43, v43
	v_pk_fma_f32 v[88:89], v[52:53], v[52:53], v[92:93] op_sel_hi:[1,1,0]
	v_pk_fma_f32 v[92:93], v[54:55], v[54:55], v[94:95] op_sel_hi:[1,1,0]
	v_pk_add_f32 v[86:87], v[86:87], v[86:87] op_sel:[0,1] op_sel_hi:[1,0]
	v_pk_add_f32 v[84:85], v[84:85], v[84:85] op_sel:[0,1] op_sel_hi:[1,0]
	v_mov_b32_e32 v89, v99
	v_mov_b32_e32 v93, v100
	v_mov_b32_e32 v87, v95
	v_mov_b32_e32 v85, v98
	v_pk_add_f32 v[88:89], v[88:89], v[92:93]
	s_waitcnt vmcnt(11)
	v_mul_f32_e32 v90, v49, v49
	v_mul_f32_e32 v91, v51, v51
	s_waitcnt vmcnt(10)
	v_mul_f32_e32 v92, v45, v45
	v_mul_f32_e32 v93, v47, v47
	v_pk_add_f32 v[84:85], v[86:87], v[84:85]
	s_waitcnt vmcnt(9)
	v_mul_f32_e32 v94, v37, v37
	v_mul_f32_e32 v95, v39, v39
	v_fmac_f32_e32 v90, v48, v48
	v_fmac_f32_e32 v91, v50, v50
	v_fmac_f32_e32 v92, v44, v44
	v_fmac_f32_e32 v93, v46, v46
	v_pk_add_f32 v[84:85], v[84:85], v[88:89]
	s_waitcnt vmcnt(8)
	v_mul_f32_e32 v96, v33, v33
	v_mul_f32_e32 v97, v35, v35
	v_fmac_f32_e32 v94, v36, v36
	v_fmac_f32_e32 v95, v38, v38
	v_add_f32_e32 v86, v90, v91
	v_add_f32_e32 v87, v92, v93
	v_add_f32_e32 v84, v84, v85
	v_fmac_f32_e32 v96, v32, v32
	v_fmac_f32_e32 v97, v34, v34
	v_add_f32_e32 v88, v94, v95
	v_add_f32_e32 v85, v86, v87
	ds_bpermute_b32 v86, v77, v84
	v_add_f32_e32 v89, v96, v97
	v_add_f32_e32 v85, v85, v88
	v_add_f32_e32 v85, v85, v89
	s_waitcnt vmcnt(7)
	v_mul_f32_e32 v88, v29, v29
	v_mul_f32_e32 v89, v31, v31
	s_waitcnt vmcnt(6)
	v_mul_f32_e32 v90, v25, v25
	v_mul_f32_e32 v91, v27, v27
	v_fmac_f32_e32 v88, v28, v28
	v_fmac_f32_e32 v89, v30, v30
	v_fmac_f32_e32 v90, v24, v24
	v_fmac_f32_e32 v91, v26, v26
	v_add_f32_e32 v88, v88, v89
	v_add_f32_e32 v89, v90, v91
	s_waitcnt lgkmcnt(0)
; __device__ __forceinline__ unsigned cvt_pk_bf16(float lo, float hi) { f32x2 v = {lo, hi}; bf16x2_t b = __builtin_convertvector(v, bf16x2_t); return __builtin_bit_cast(unsigned, b); }
; __device__ __forceinline__ void prep_phase(const Args& a, LAS unsigned char* lds, int vcu, int G, int wave, int lane) {
;     ...
; #pragma unroll
;         for (int r = 0; r < 4; ++r) { float t = 0.f;
; #pragma unroll
;             for (int j = 0; j < 4; ++j) t += (v[r][j][0] * v[r][j][0] + v[r][j][1] * v[r][j][1]) + (v[r][j][2] * v[r][j][2] + v[r][j][3] * v[r][j][3]);
;             s[r] = wave_sum(t); }
; #pragma unroll
;         for (int r = 0; r < 4; ++r) { const int mr = m + r * NGW;
;             const float ri = __builtin_amdgcn_rsqf(s[r] * (1.0f / 1024.0f) + RMS_EPS);
;             if (mr < MTOK) { u32x2* o8 = (u32x2*)(XB + (size_t)mr * DM) + lane;
; #pragma unroll
;                 for (int j = 0; j < 4; ++j) { u32x2 w; w.x = cvt_pk_bf16(v[r][j][0] * ri, v[r][j][1] * ri); w.y = cvt_pk_bf16(v[r][j][2] * ri, v[r][j][3] * ri); o8[64 * j] = w; } } }
	v_add_f32_e32 v84, v84, v86
	s_waitcnt vmcnt(5)
	v_mul_f32_e32 v92, v21, v21
	v_add_f32_e32 v88, v88, v89
	v_mul_f32_e32 v89, v23, v23
	ds_bpermute_b32 v86, v78, v84
	v_fmac_f32_e32 v92, v20, v20
	v_fmac_f32_e32 v89, v22, v22
	v_add_f32_e32 v89, v92, v89
	v_add_f32_e32 v88, v88, v89
	s_waitcnt vmcnt(4)
	v_mul_f32_e32 v89, v17, v17
	v_mul_f32_e32 v90, v19, v19
	v_fmac_f32_e32 v89, v16, v16
	v_fmac_f32_e32 v90, v18, v18
	v_add_f32_e32 v89, v89, v90
	s_waitcnt lgkmcnt(0)
	v_add_f32_e32 v84, v84, v86
	v_add_f32_e32 v88, v88, v89
	ds_bpermute_b32 v87, v77, v85
	ds_bpermute_b32 v86, v79, v84
	ds_bpermute_b32 v89, v77, v88
	s_waitcnt vmcnt(3)
	v_mul_f32_e32 v90, v15, v15
	v_fmac_f32_e32 v90, v14, v14
	s_waitcnt lgkmcnt(2)
	v_add_f32_e32 v85, v85, v87
	s_waitcnt lgkmcnt(1)
	v_add_f32_e32 v84, v84, v86
	s_waitcnt lgkmcnt(0)
	v_add_f32_e32 v87, v88, v89
	v_mul_f32_e32 v89, v13, v13
	ds_bpermute_b32 v86, v80, v84
	v_fmac_f32_e32 v89, v12, v12
	v_add_f32_e32 v89, v89, v90
	s_waitcnt vmcnt(2)
	v_mul_f32_e32 v90, v9, v9
	v_mul_f32_e32 v91, v11, v11
	v_fmac_f32_e32 v90, v8, v8
	v_fmac_f32_e32 v91, v10, v10
	v_add_f32_e32 v90, v90, v91
	v_add_f32_e32 v89, v89, v90
	s_waitcnt vmcnt(1)
	v_mul_f32_e32 v90, v5, v5
	v_mul_f32_e32 v91, v7, v7
	s_waitcnt lgkmcnt(0)
	v_add_f32_e32 v84, v84, v86
	v_fmac_f32_e32 v90, v4, v4
	v_fmac_f32_e32 v91, v6, v6
	ds_bpermute_b32 v86, v81, v84
	v_add_f32_e32 v90, v90, v91
	v_add_f32_e32 v89, v89, v90
	s_waitcnt vmcnt(0)
	v_mul_f32_e32 v90, v1, v1
	v_mul_f32_e32 v91, v3, v3
	v_fmac_f32_e32 v90, v0, v0
	v_fmac_f32_e32 v91, v2, v2
	v_add_f32_e32 v90, v90, v91
	v_add_f32_e32 v89, v89, v90
	s_waitcnt lgkmcnt(0)
	v_add_f32_e32 v84, v84, v86
	ds_bpermute_b32 v86, v78, v85
	ds_bpermute_b32 v90, v77, v89
	ds_bpermute_b32 v88, v78, v87
	ds_bpermute_b32 v93, v82, v84
	s_waitcnt lgkmcnt(3)
	v_add_f32_e32 v85, v85, v86
	s_waitcnt lgkmcnt(2)
	v_add_f32_e32 v89, v89, v90
	ds_bpermute_b32 v86, v79, v85
	s_waitcnt lgkmcnt(2)
	v_add_f32_e32 v87, v87, v88
	ds_bpermute_b32 v90, v78, v89
	ds_bpermute_b32 v88, v79, v87
	s_waitcnt lgkmcnt(3)
	v_add_f32_e32 v84, v84, v93
	s_waitcnt lgkmcnt(2)
	v_add_f32_e32 v85, v85, v86
	ds_bpermute_b32 v86, v80, v85
	s_waitcnt lgkmcnt(2)
	v_add_f32_e32 v89, v89, v90
	s_waitcnt lgkmcnt(1)
	v_add_f32_e32 v87, v87, v88
	ds_bpermute_b32 v90, v79, v89
	ds_bpermute_b32 v88, v80, v87
	s_waitcnt lgkmcnt(2)
	v_add_f32_e32 v85, v85, v86
	ds_bpermute_b32 v86, v81, v85
	v_fmamk_f32 v84, v84, 0x3a800000, v83
	s_waitcnt lgkmcnt(2)
	v_add_f32_e32 v90, v89, v90
	s_waitcnt lgkmcnt(1)
	v_add_f32_e32 v87, v87, v88
	ds_bpermute_b32 v92, v80, v90
	ds_bpermute_b32 v91, v81, v87
	s_waitcnt lgkmcnt(2)
	v_add_f32_e32 v88, v85, v86
	ds_bpermute_b32 v89, v82, v88
	s_waitcnt lgkmcnt(2)
	v_add_f32_e32 v85, v90, v92
	s_waitcnt lgkmcnt(1)
	v_add_f32_e32 v86, v87, v91
	ds_bpermute_b32 v91, v81, v85
	v_rsq_f32_e32 v90, v84
	ds_bpermute_b32 v87, v82, v86
	v_lshl_add_u64 v[92:93], v[66:67], 0, s[12:13]
	s_waitcnt lgkmcnt(1)
	v_add_f32_e32 v84, v85, v91
	ds_bpermute_b32 v85, v82, v84
	v_pk_mul_f32 v[60:61], v[60:61], v[90:91] op_sel_hi:[1,0]
	v_pk_mul_f32 v[62:63], v[62:63], v[90:91] op_sel_hi:[1,0]
	v_pk_mul_f32 v[56:57], v[56:57], v[90:91] op_sel_hi:[1,0]
	v_pk_mul_f32 v[58:59], v[58:59], v[90:91] op_sel_hi:[1,0]
	v_pk_mul_f32 v[52:53], v[52:53], v[90:91] op_sel_hi:[1,0]
	v_pk_mul_f32 v[54:55], v[54:55], v[90:91] op_sel_hi:[1,0]
	v_pk_mul_f32 v[40:41], v[40:41], v[90:91] op_sel_hi:[1,0]
	v_pk_mul_f32 v[42:43], v[42:43], v[90:91] op_sel_hi:[1,0]
	v_cvt_pk_bf16_f32 v60, v60, v61
	v_cvt_pk_bf16_f32 v61, v62, v63
	v_cvt_pk_bf16_f32 v56, v56, v57
	v_cvt_pk_bf16_f32 v57, v58, v59
	v_cvt_pk_bf16_f32 v52, v52, v53
	v_cvt_pk_bf16_f32 v53, v54, v55
	v_cvt_pk_bf16_f32 v40, v40, v41
	v_cvt_pk_bf16_f32 v41, v42, v43
	global_store_dwordx2 v[92:93], v[60:61], off sc1
	global_store_dwordx2 v[92:93], v[56:57], off offset:512 sc1
	global_store_dwordx2 v[92:93], v[52:53], off offset:1024 sc1
	global_store_dwordx2 v[92:93], v[40:41], off offset:1536 sc1
	s_cbranch_scc0 .LBB0_299
	s_andn2_b64 vcc, exec, s[10:11]
	s_cbranch_vccz .LBB0_300

; __device__ __forceinline__ unsigned cvt_pk_bf16(float lo, float hi) { f32x2 v = {lo, hi}; bf16x2_t b = __builtin_convertvector(v, bf16x2_t); return __builtin_bit_cast(unsigned, b); }
; __device__ __forceinline__ void prep_phase(const Args& a, LAS unsigned char* lds, int vcu, int G, int wave, int lane) {
;     ...
;         for (int r = 0; r < 4; ++r) { const int mr = m + r * NGW;
;             const float ri = __builtin_amdgcn_rsqf(s[r] * (1.0f / 1024.0f) + RMS_EPS);
;             if (mr < MTOK) { u32x2* o8 = (u32x2*)(XB + (size_t)mr * DM) + lane;
; #pragma unroll
;                 for (int j = 0; j < 4; ++j) { u32x2 w; w.x = cvt_pk_bf16(v[r][j][0] * ri, v[r][j][1] * ri); w.y = cvt_pk_bf16(v[r][j][2] * ri, v[r][j][3] * ri); o8[64 * j] = w; } } }
.LBB0_299:
	v_add_f32_e32 v40, v88, v89
	v_fmamk_f32 v40, v40, 0x3a800000, v83
	v_rsq_f32_e32 v40, v40
	s_ashr_i32 s3, s2, 31
	s_lshl_b64 s[12:13], s[2:3], 11
	v_lshl_add_u64 v[42:43], v[66:67], 0, s[12:13]
	v_pk_mul_f32 v[48:49], v[48:49], v[40:41] op_sel_hi:[1,0]
	v_pk_mul_f32 v[50:51], v[50:51], v[40:41] op_sel_hi:[1,0]
	v_pk_mul_f32 v[44:45], v[44:45], v[40:41] op_sel_hi:[1,0]
	v_pk_mul_f32 v[46:47], v[46:47], v[40:41] op_sel_hi:[1,0]
	v_pk_mul_f32 v[36:37], v[36:37], v[40:41] op_sel_hi:[1,0]
	v_pk_mul_f32 v[38:39], v[38:39], v[40:41] op_sel_hi:[1,0]
	v_pk_mul_f32 v[32:33], v[32:33], v[40:41] op_sel_hi:[1,0]
	v_pk_mul_f32 v[34:35], v[34:35], v[40:41] op_sel_hi:[1,0]
	v_cvt_pk_bf16_f32 v48, v48, v49
	v_cvt_pk_bf16_f32 v49, v50, v51
	v_cvt_pk_bf16_f32 v44, v44, v45
	v_cvt_pk_bf16_f32 v45, v46, v47
	v_cvt_pk_bf16_f32 v36, v36, v37
	v_cvt_pk_bf16_f32 v37, v38, v39
	v_cvt_pk_bf16_f32 v32, v32, v33
	v_cvt_pk_bf16_f32 v33, v34, v35
	global_store_dwordx2 v[42:43], v[48:49], off sc1
	global_store_dwordx2 v[42:43], v[44:45], off offset:512 sc1
	global_store_dwordx2 v[42:43], v[36:37], off offset:1024 sc1
	global_store_dwordx2 v[42:43], v[32:33], off offset:1536 sc1
	s_andn2_b64 vcc, exec, s[10:11]
	s_cbranch_vccnz .LBB0_298
.LBB0_300:
	s_waitcnt lgkmcnt(1)
	v_add_f32_e32 v32, v86, v87
	v_fmamk_f32 v32, v32, 0x3a800000, v83
	v_rsq_f32_e32 v32, v32
	s_ashr_i32 s9, s8, 31
	s_lshl_b64 s[8:9], s[8:9], 11
	v_lshl_add_u64 v[34:35], v[66:67], 0, s[8:9]
	v_pk_mul_f32 v[28:29], v[28:29], v[32:33] op_sel_hi:[1,0]
	v_pk_mul_f32 v[30:31], v[30:31], v[32:33] op_sel_hi:[1,0]
	v_pk_mul_f32 v[24:25], v[24:25], v[32:33] op_sel_hi:[1,0]
	v_pk_mul_f32 v[26:27], v[26:27], v[32:33] op_sel_hi:[1,0]
	v_pk_mul_f32 v[20:21], v[20:21], v[32:33] op_sel_hi:[1,0]
	v_pk_mul_f32 v[22:23], v[22:23], v[32:33] op_sel_hi:[1,0]
	v_pk_mul_f32 v[16:17], v[16:17], v[32:33] op_sel_hi:[1,0]
	v_pk_mul_f32 v[18:19], v[18:19], v[32:33] op_sel_hi:[1,0]
	v_cvt_pk_bf16_f32 v28, v28, v29
	v_cvt_pk_bf16_f32 v29, v30, v31
	v_cvt_pk_bf16_f32 v24, v24, v25
	v_cvt_pk_bf16_f32 v25, v26, v27
	v_cvt_pk_bf16_f32 v20, v20, v21
	v_cvt_pk_bf16_f32 v21, v22, v23
	v_cvt_pk_bf16_f32 v16, v16, v17
	v_cvt_pk_bf16_f32 v17, v18, v19
	global_store_dwordx2 v[34:35], v[28:29], off sc1
	global_store_dwordx2 v[34:35], v[24:25], off offset:512 sc1
	global_store_dwordx2 v[34:35], v[20:21], off offset:1024 sc1
	global_store_dwordx2 v[34:35], v[16:17], off offset:1536 sc1
	s_andn2_b64 vcc, exec, s[6:7]
	s_cbranch_vccnz .LBB0_295
.LBB0_301:
	s_waitcnt lgkmcnt(0)
	v_add_f32_e32 v16, v84, v85
	v_fmamk_f32 v16, v16, 0x3a800000, v83
	v_rsq_f32_e32 v16, v16
	s_ashr_i32 s5, s4, 31
	s_lshl_b64 s[4:5], s[4:5], 11
	v_lshl_add_u64 v[18:19], v[66:67], 0, s[4:5]
	v_pk_mul_f32 v[12:13], v[12:13], v[16:17] op_sel_hi:[1,0]
	v_pk_mul_f32 v[14:15], v[14:15], v[16:17] op_sel_hi:[1,0]
	v_pk_mul_f32 v[8:9], v[8:9], v[16:17] op_sel_hi:[1,0]
	v_pk_mul_f32 v[10:11], v[10:11], v[16:17] op_sel_hi:[1,0]
	v_pk_mul_f32 v[4:5], v[4:5], v[16:17] op_sel_hi:[1,0]
	v_pk_mul_f32 v[6:7], v[6:7], v[16:17] op_sel_hi:[1,0]
	v_pk_mul_f32 v[0:1], v[0:1], v[16:17] op_sel_hi:[1,0]
	v_pk_mul_f32 v[2:3], v[2:3], v[16:17] op_sel_hi:[1,0]
	v_cvt_pk_bf16_f32 v12, v12, v13
	v_cvt_pk_bf16_f32 v13, v14, v15
	v_cvt_pk_bf16_f32 v8, v8, v9
	v_cvt_pk_bf16_f32 v9, v10, v11
	v_cvt_pk_bf16_f32 v4, v4, v5
	v_cvt_pk_bf16_f32 v5, v6, v7
	v_cvt_pk_bf16_f32 v0, v0, v1
	v_cvt_pk_bf16_f32 v1, v2, v3
	global_store_dwordx2 v[18:19], v[12:13], off sc1
	global_store_dwordx2 v[18:19], v[8:9], off offset:512 sc1
	global_store_dwordx2 v[18:19], v[4:5], off offset:1024 sc1
	global_store_dwordx2 v[18:19], v[0:1], off offset:1536 sc1
	s_branch .LBB0_295

; __device__ __forceinline__ void prep_phase(const Args& a, LAS unsigned char* lds, int vcu, int G, int wave, int lane) {
;     ...
;     { float* TAB = (float*)(ws + WS_TAB); const float* tbl = a.in[23];
;       for (int i = gw * 64 + lane; i < 8 * 128; i += NGW * 64) { const int h = i >> 7, d = i & 127; TAB[i] = tbl[(int)T5_BUCKET[d] * 8 + h] * LOG2E; } }
.LBB0_304:
	v_and_b32_e32 v1, 0x7f, v0
	global_load_ubyte v1, v1, s[12:13]
	v_ashrrev_i32_e32 v4, 7, v0
	v_add_u32_e32 v0, s6, v0
	v_cmp_lt_i32_e32 vcc, s0, v0
	s_or_b64 s[10:11], vcc, s[10:11]
	s_waitcnt vmcnt(0)
	v_lshl_add_u32 v4, v1, 3, v4
	v_ashrrev_i32_e32 v5, 31, v4
	v_lshl_add_u64 v[4:5], v[4:5], 2, s[4:5]
	global_load_dword v1, v[4:5], off
	s_waitcnt vmcnt(0)
	v_mul_f32_e32 v1, 0x3fb8aa3b, v1
	global_store_dword v[2:3], v1, off sc1
	v_lshl_add_u64 v[2:3], v[2:3], 0, s[8:9]
	s_andn2_b64 exec, exec, s[10:11]
	s_cbranch_execnz .LBB0_304

; __device__ __forceinline__ void prep_phase(const Args& a, LAS unsigned char* lds, int vcu, int G, int wave, int lane) {
;     ...
;     { float* C1 = (float*)(ws + WS_C1);
;       for (int o = gw; o < 256; o += NGW) { const int kv = o >> 7, n = o & 127; const float* pos = a.in[11 + kv]; const float* w1 = a.in[13 + 2 * kv]; float s = 0.f;
;           for (int k = lane; k < 2048; k += 64) s += pos[k] * w1[(size_t)k * 128 + n];
;           s = wave_sum(s); if (lane == 0) C1[o] = s; } }
.LBB0_309:
	global_load_dword v17, v[4:5], off
	global_load_dword v18, v[6:7], off
	v_add_u32_e32 v16, 64, v16
	v_cmp_lt_u32_e64 s[2:3], s13, v16
	v_lshl_add_u64 v[4:5], v[4:5], 0, s[6:7]
	v_lshl_add_u64 v[6:7], v[6:7], 0, s[8:9]
	s_or_b64 s[10:11], s[2:3], s[10:11]
	s_waitcnt vmcnt(0)
	v_fmac_f32_e32 v15, v17, v18
	s_andn2_b64 exec, exec, s[10:11]
	s_cbranch_execnz .LBB0_309
	s_or_b64 exec, exec, s[10:11]
	ds_bpermute_b32 v4, v8, v15
	s_waitcnt lgkmcnt(0)
	v_add_f32_e32 v4, v15, v4
	ds_bpermute_b32 v5, v9, v4
	s_waitcnt lgkmcnt(0)
	v_add_f32_e32 v4, v4, v5
	ds_bpermute_b32 v5, v10, v4
	s_waitcnt lgkmcnt(0)
	v_add_f32_e32 v4, v4, v5
	ds_bpermute_b32 v5, v11, v4
	s_waitcnt lgkmcnt(0)
	v_add_f32_e32 v4, v4, v5
	ds_bpermute_b32 v5, v12, v4
	s_waitcnt lgkmcnt(0)
	v_add_f32_e32 v4, v4, v5
	ds_bpermute_b32 v5, v13, v4
	s_and_saveexec_b64 s[2:3], vcc
	s_cbranch_execz .LBB0_307
	s_ashr_i32 s37, s36, 31
	s_lshl_b64 s[10:11], s[36:37], 2
	s_add_u32 s10, s0, s10
	s_waitcnt lgkmcnt(0)
	v_add_f32_e32 v4, v4, v5
	s_addc_u32 s11, s1, s11
	global_store_dword v1, v4, s[10:11] sc1
	s_branch .LBB0_307
